# accumulator zero-init with v_mov_b64 (half the moves) in every GEMM tile loop
# baseline (speedup 1.0000x reference)
;     __device__ __forceinline__ long offA(const Unit& u) const { return (long)(u.z / zdiv) * sAo + (long)(u.z % zdiv) * sAi + (long)u.pm * BM * lda; }
;     __device__ __forceinline__ long offB(const Unit& u) const { return (long)(u.z / zdiv) * sBo + (long)(u.z % zdiv) * sBi + (long)u.pn * BM * ldb; }
; template <class Epi, bool ALIGN_EPI>
; __device__ __forceinline__ void gemm_phase(LAS unsigned char* lds, LAS unsigned char* xl, const Gemm g, const Order& S, Epi& E) {
;     ...
;         const bool has_next = S.next(ui + 1, nxt);
;         const char* nA = has_next ? (const char*)g.A + 2 * g.offA(nxt) : cA; const char* nB = has_next ? (const char*)g.Bt + 2 * g.offB(nxt) : cB;
;     ...
;         for (int a = 0; a < 2; ++a)
; #pragma unroll
;             for (int b = 0; b < 2; ++b)
; #pragma unroll
;                 for (int m = 0; m < 4; ++m)
; #pragma unroll
;                     for (int n = 0; n < 2; ++n) acc[a][b][m][n] = (f32x4){0.f, 0.f, 0.f, 0.f};
;         cur = nxt; cA = nA; cB = nB; ++ui;
.LBB0_360:
	s_ashr_i32 s17, s16, 31
	s_lshl_b64 s[22:23], s[16:17], 19
	v_readlane_b32 s24, v253, 21
	v_readlane_b32 s25, v253, 22
	s_add_u32 s22, s24, s22
	s_addc_u32 s23, s25, s23
	s_and_b64 s[24:25], s[0:1], exec
	s_cselect_b32 s17, s23, s27
	s_cselect_b32 s47, s22, s26
	s_ashr_i32 s21, s20, 31
	s_lshl_b64 s[24:25], s[20:21], 19
	s_add_u32 s24, s6, s24
	s_addc_u32 s25, s7, s25
	s_and_b64 s[30:31], s[0:1], exec
	s_cselect_b32 s21, s25, s29
	s_cselect_b32 s48, s24, s28
	s_add_u32 s26, s26, 0x40080
	s_addc_u32 s27, s27, 0
	s_add_u32 s49, s28, 0x100
	v_mov_b32_e32 v0, 0
	s_addc_u32 s50, s29, 0
	s_mov_b32 s51, -2
	v_mov_b32_e32 v1, v0
	v_mov_b64_e32 v[2:3], 0
	v_mov_b64_e32 v[4:5], 0
	v_mov_b64_e32 v[6:7], 0
	v_mov_b64_e32 v[8:9], 0
	v_mov_b64_e32 v[10:11], 0
	v_mov_b64_e32 v[12:13], 0
	v_mov_b64_e32 v[14:15], 0
	v_mov_b64_e32 v[24:25], 0
	v_mov_b64_e32 v[26:27], 0
	v_mov_b64_e32 v[28:29], 0
	v_mov_b64_e32 v[30:31], 0
	v_mov_b64_e32 v[40:41], 0
	v_mov_b64_e32 v[42:43], 0
	v_mov_b64_e32 v[44:45], 0
	v_mov_b64_e32 v[46:47], 0
	v_mov_b64_e32 v[16:17], 0
	v_mov_b64_e32 v[18:19], 0
	v_mov_b64_e32 v[20:21], 0
	v_mov_b64_e32 v[22:23], 0
	v_mov_b64_e32 v[32:33], 0
	v_mov_b64_e32 v[34:35], 0
	v_mov_b64_e32 v[36:37], 0
	v_mov_b64_e32 v[38:39], 0
	v_mov_b64_e32 v[48:49], 0
	v_mov_b64_e32 v[50:51], 0
	v_mov_b64_e32 v[52:53], 0
	v_mov_b64_e32 v[54:55], 0
	v_mov_b64_e32 v[56:57], 0
	v_mov_b64_e32 v[58:59], 0
	v_mov_b64_e32 v[60:61], 0
	v_mov_b64_e32 v[62:63], 0
	v_mov_b64_e32 v[64:65], 0
	v_mov_b64_e32 v[66:67], 0
	v_mov_b64_e32 v[68:69], 0
	v_mov_b64_e32 v[70:71], 0
	v_mov_b64_e32 v[72:73], 0
	v_mov_b64_e32 v[74:75], 0
	v_mov_b64_e32 v[76:77], 0
	v_mov_b64_e32 v[78:79], 0
	v_mov_b64_e32 v[88:89], 0
	v_mov_b64_e32 v[90:91], 0
	v_mov_b64_e32 v[92:93], 0
	v_mov_b64_e32 v[94:95], 0
	v_mov_b64_e32 v[104:105], 0
	v_mov_b64_e32 v[106:107], 0
	v_mov_b64_e32 v[108:109], 0
	v_mov_b64_e32 v[110:111], 0
	v_mov_b64_e32 v[80:81], 0
	v_mov_b64_e32 v[82:83], 0
	v_mov_b64_e32 v[84:85], 0
	v_mov_b64_e32 v[86:87], 0
	v_mov_b64_e32 v[96:97], 0
	v_mov_b64_e32 v[98:99], 0
	v_mov_b64_e32 v[100:101], 0
	v_mov_b64_e32 v[102:103], 0
	v_mov_b64_e32 v[112:113], 0
	v_mov_b64_e32 v[114:115], 0
	v_mov_b64_e32 v[116:117], 0
	v_mov_b64_e32 v[118:119], 0
	v_mov_b64_e32 v[120:121], 0
	v_mov_b64_e32 v[122:123], 0
	v_mov_b64_e32 v[124:125], 0
	v_mov_b64_e32 v[126:127], 0

; template <class Epi, bool ALIGN_EPI>
; __device__ __forceinline__ void gemm_phase(LAS unsigned char* lds, LAS unsigned char* xl, const Gemm g, const Order& S, Epi& E) {
;     ...
;         for (int a = 0; a < 2; ++a)
; #pragma unroll
;             for (int b = 0; b < 2; ++b)
; #pragma unroll
;                 for (int m = 0; m < 4; ++m)
; #pragma unroll
;                     for (int n = 0; n < 2; ++n) acc[a][b][m][n] = (f32x4){0.f, 0.f, 0.f, 0.f};
;         cur = nxt; cA = nA; cB = nB; ++ui;
.LBB0_384:
	s_add_u32 s38, s38, 0x40080
	s_addc_u32 s39, s39, 0
	s_add_u32 s25, s40, 0x100
	v_mov_b32_e32 v0, 0
	s_addc_u32 s27, s41, 0
	s_mov_b32 s29, -2
	v_mov_b32_e32 v1, v0
	v_mov_b64_e32 v[2:3], 0
	v_mov_b64_e32 v[4:5], 0
	v_mov_b64_e32 v[6:7], 0
	v_mov_b64_e32 v[8:9], 0
	v_mov_b64_e32 v[10:11], 0
	v_mov_b64_e32 v[12:13], 0
	v_mov_b64_e32 v[14:15], 0
	v_mov_b64_e32 v[24:25], 0
	v_mov_b64_e32 v[26:27], 0
	v_mov_b64_e32 v[28:29], 0
	v_mov_b64_e32 v[30:31], 0
	v_mov_b64_e32 v[40:41], 0
	v_mov_b64_e32 v[42:43], 0
	v_mov_b64_e32 v[44:45], 0
	v_mov_b64_e32 v[46:47], 0
	v_mov_b64_e32 v[16:17], 0
	v_mov_b64_e32 v[18:19], 0
	v_mov_b64_e32 v[20:21], 0
	v_mov_b64_e32 v[22:23], 0
	v_mov_b64_e32 v[32:33], 0
	v_mov_b64_e32 v[34:35], 0
	v_mov_b64_e32 v[36:37], 0
	v_mov_b64_e32 v[38:39], 0
	v_mov_b64_e32 v[48:49], 0
	v_mov_b64_e32 v[50:51], 0
	v_mov_b64_e32 v[52:53], 0
	v_mov_b64_e32 v[54:55], 0
	v_mov_b64_e32 v[56:57], 0
	v_mov_b64_e32 v[58:59], 0
	v_mov_b64_e32 v[60:61], 0
	v_mov_b64_e32 v[62:63], 0
	v_mov_b64_e32 v[64:65], 0
	v_mov_b64_e32 v[66:67], 0
	v_mov_b64_e32 v[68:69], 0
	v_mov_b64_e32 v[70:71], 0
	v_mov_b64_e32 v[72:73], 0
	v_mov_b64_e32 v[74:75], 0
	v_mov_b64_e32 v[76:77], 0
	v_mov_b64_e32 v[78:79], 0
	v_mov_b64_e32 v[88:89], 0
	v_mov_b64_e32 v[90:91], 0
	v_mov_b64_e32 v[92:93], 0
	v_mov_b64_e32 v[94:95], 0
	v_mov_b64_e32 v[104:105], 0
	v_mov_b64_e32 v[106:107], 0
	v_mov_b64_e32 v[108:109], 0
	v_mov_b64_e32 v[110:111], 0
	v_mov_b64_e32 v[80:81], 0
	v_mov_b64_e32 v[82:83], 0
	v_mov_b64_e32 v[84:85], 0
	v_mov_b64_e32 v[86:87], 0
	v_mov_b64_e32 v[96:97], 0
	v_mov_b64_e32 v[98:99], 0
	v_mov_b64_e32 v[100:101], 0
	v_mov_b64_e32 v[102:103], 0
	v_mov_b64_e32 v[112:113], 0
	v_mov_b64_e32 v[114:115], 0
	v_mov_b64_e32 v[116:117], 0
	v_mov_b64_e32 v[118:119], 0
	v_mov_b64_e32 v[120:121], 0
	v_mov_b64_e32 v[122:123], 0
	v_mov_b64_e32 v[124:125], 0
	v_mov_b64_e32 v[126:127], 0

; #define LAS __attribute__((address_space(3)))
; __device__ __forceinline__ void rwkv_chain(LAS unsigned char* lds, int cid, const bf16_t* P0, const float* mu, const float* w0, const float* w2, const float* a0, const float* a2, ...
;     ...
;     const int vt = wid >> 1, tt2 = wid & 1;
;     f32x4 st[2]; st[0] = (f32x4){0.f, 0.f, 0.f, 0.f}; st[1] = st[0];
;     __syncthreads();
;     const bf16_t* Pb = P0 + (size_t)b * SEQ * ABPAD;
;     u32x2 rc[5], rpv[5], rnx[5]; unsigned short gcv = 0, gpv = 0, gnv = 0;
;     const unsigned voff = (unsigned)((((int)threadIdx.x >> 4) * ABPAD + ((int)threadIdx.x & 15) * 4) * 2);
;     ...
;     RW_ISSUE(dir ? 127 * 32 : 0);
;     for (int cc = 0; cc < 128; ++cc) {
;         const int t0 = dir ? (127 - cc) * 32 : cc * 32;
;         { RW_IDS
;         { const int tok = tid >> 4, c4 = (tid & 15) * 4;
; #pragma unroll
;         for (int i = 0; i < 5; ++i) {
;             const f32x4 mu4 = *(const LAS f32x4*)(cst + (5 + i) * 64 + c4);
.LBB0_486:
	s_lshl_b64 s[40:41], s[12:13], 12
	s_lshl_b64 s[2:3], s[38:39], 1
	s_add_u32 s42, s57, s2
	s_addc_u32 s43, s63, s3
	s_lshl_b32 s1, s1, 2
	v_readlane_b32 s2, v253, 30
	v_readlane_b32 s3, v253, 31
	s_add_u32 s44, s2, s1
	s_addc_u32 s45, s3, 0
	s_and_b64 s[2:3], s[10:11], exec
	s_cselect_b32 s90, 1, -1
	s_lshl_b32 s1, s87, 26
	v_readlane_b32 s2, v253, 21
	v_readlane_b32 s3, v253, 22
	s_add_u32 s1, s2, s1
	s_addc_u32 s2, s3, 0
	s_lshl_b32 s0, s0, 1
	s_add_u32 s91, s1, s0
	s_addc_u32 s92, s2, 0
	s_and_b64 s[0:1], s[10:11], exec
	s_movk_i32 s8, 0x1e00
	s_movk_i32 s9, 0x1d00
	s_movk_i32 s12, 0x1b00
	s_movk_i32 s13, 0x1a00
	s_movk_i32 s14, 0x1900
	s_movk_i32 s15, 0x1800
	s_movk_i32 s16, 0x1700
	s_movk_i32 s17, 0x1600
	s_movk_i32 s46, 0x1500
	s_movk_i32 s47, 0x1400
	s_movk_i32 s48, 0x1300
	s_movk_i32 s49, 0x1200
	s_movk_i32 s5, 0x1100
	s_cselect_b32 s93, 0x1f00, 0
	s_cselect_b32 s94, s8, 0x100
	s_cselect_b32 s95, s9, 0x200
	s_cselect_b32 s96, s62, 0x300
	s_cselect_b32 s97, s12, 0x400
	s_cselect_b32 s22, s13, 0x500
	s_cselect_b32 s23, s14, 0x600
	s_cselect_b32 s18, s15, 0x700
	s_cselect_b32 s19, s16, 0x800
	s_cselect_b32 s2, s17, 0x900
	s_cselect_b32 s3, s46, 0xa00
	s_cselect_b32 s56, s47, 0xb00
	s_cselect_b32 s57, s48, 0xc00
	s_cselect_b32 s0, s49, 0xd00
	s_cselect_b32 s1, s5, 0xe00
	s_lshl_b32 s4, s87, 8
	s_and_b64 s[6:7], s[10:11], exec
	s_cselect_b32 s5, 0xe00, s5
	s_cselect_b32 s60, 0xd00, s49
	s_cselect_b32 s61, 0xc00, s48
	s_cselect_b32 s63, 0xb00, s47
	s_cselect_b32 s64, 0xa00, s46
	s_cselect_b32 s65, 0x900, s17
	s_cselect_b32 s66, 0x800, s16
	s_cselect_b32 s67, 0x700, s15
	s_cselect_b32 s68, 0x600, s14
	s_cselect_b32 s69, 0x500, s13
	s_cselect_b32 s70, 0x400, s12
	s_cselect_b32 s71, 0x300, s62
	s_cselect_b32 s72, 0x200, s9
	s_cselect_b32 s73, 0x100, s8
	s_cselect_b32 s8, 0, 0x1f00
	s_sub_i32 s9, 0, s4
	s_mov_b64 s[46:47], 0
	s_movk_i32 s6, 0xfc0
	v_mov_b32_e32 v1, v0
	v_mov_b64_e32 v[2:3], 0
	v_mov_b64_e32 v[4:5], 0
	v_mov_b64_e32 v[6:7], 0
	v_and_b32_e32 v9, 15, v200
	v_lshl_add_u32 v8, v9, 4, s33
	v_lshl_add_u32 v9, v9, 2, s33
	ds_read_b128 v[232:235], v8
	ds_read_b128 v[236:239], v8 offset:256
	ds_read_b128 v[240:243], v8 offset:512
	ds_read_b128 v[244:247], v8 offset:768
	ds_read_b128 v[248:251], v8 offset:1024
	ds_read_b128 v[210:213], v8 offset:1280
	ds_read_b128 v[214:217], v8 offset:1536
	ds_read_b128 v[218:221], v8 offset:1792
	ds_read_b128 v[222:225], v8 offset:2048
	ds_read_b128 v[226:229], v8 offset:2304
	ds_read_b32 v230, v9 offset:2560
	s_waitcnt vmcnt(0) lgkmcnt(0)
	s_branch .LBB0_489

; __device__ __forceinline__ void ssd_s1_unit(LAS unsigned char* lds, int unit, const bf16_t* P0, const float* cw, const float* cb, const float* dt_bias, const float* a_log, bf16_t* STATES, float* TOT) {
;     ...
;     for (int d = 0; d < 2; ++d) {
;         f32x4 acc[2][8];
; #pragma unroll
;         for (int mt = 0; mt < 2; ++mt)
; #pragma unroll
;             for (int nt = 0; nt < 8; ++nt) acc[mt][nt] = (f32x4){0.f, 0.f, 0.f, 0.f};
; #pragma unroll 1
;         for (int ks = 0; ks < 4; ++ks) {
.LBB0_648:
	v_mov_b32_e32 v0, 0
	s_xor_b64 s[24:25], s[26:27], -1
	v_lshl_add_u32 v66, s16, 9, v123
	s_mov_b32 s26, 4
	v_mov_b32_e32 v67, v122
	v_mov_b32_e32 v68, v121
	v_mov_b32_e32 v1, v0
	v_mov_b64_e32 v[2:3], 0
	v_mov_b64_e32 v[4:5], 0
	v_mov_b64_e32 v[6:7], 0
	v_mov_b64_e32 v[8:9], 0
	v_mov_b64_e32 v[10:11], 0
	v_mov_b64_e32 v[12:13], 0
	v_mov_b64_e32 v[14:15], 0
	v_mov_b64_e32 v[16:17], 0
	v_mov_b64_e32 v[18:19], 0
	v_mov_b64_e32 v[20:21], 0
	v_mov_b64_e32 v[22:23], 0
	v_mov_b64_e32 v[32:33], 0
	v_mov_b64_e32 v[34:35], 0
	v_mov_b64_e32 v[36:37], 0
	v_mov_b64_e32 v[38:39], 0
	v_mov_b64_e32 v[40:41], 0
	v_mov_b64_e32 v[42:43], 0
	v_mov_b64_e32 v[44:45], 0
	v_mov_b64_e32 v[46:47], 0
	v_mov_b64_e32 v[48:49], 0
	v_mov_b64_e32 v[50:51], 0
	v_mov_b64_e32 v[52:53], 0
	v_mov_b64_e32 v[54:55], 0
	v_mov_b64_e32 v[56:57], 0
	v_mov_b64_e32 v[58:59], 0
	v_mov_b64_e32 v[60:61], 0
	v_mov_b64_e32 v[62:63], 0
	v_mov_b64_e32 v[28:29], 0
	v_mov_b64_e32 v[30:31], 0
	v_mov_b64_e32 v[24:25], 0
	v_mov_b64_e32 v[26:27], 0

; template <class Epi, bool ALIGN_EPI>
; __device__ __forceinline__ void gemm_phase(LAS unsigned char* lds, LAS unsigned char* xl, const Gemm g, const Order& S, Epi& E) {
;     ...
;     f32x4 acc[2][2][4][2];
; #pragma unroll
;     for (int a = 0; a < 2; ++a)
; #pragma unroll
;         for (int b = 0; b < 2; ++b)
; #pragma unroll
;             for (int m = 0; m < 4; ++m)
; #pragma unroll
;                 for (int n = 0; n < 2; ++n) acc[a][b][m][n] = (f32x4){0.f, 0.f, 0.f, 0.f};
;     ...
;         for (int a = 0; a < 2; ++a)
; #pragma unroll
;             for (int b = 0; b < 2; ++b)
; #pragma unroll
;                 for (int m = 0; m < 4; ++m)
; #pragma unroll
;                     for (int n = 0; n < 2; ++n) acc[a][b][m][n] = (f32x4){0.f, 0.f, 0.f, 0.f};
;         cur = nxt; cA = nA; cB = nB; ++ui;
.LBB0_720:
	s_ashr_i32 s17, s16, 31
	s_lshl_b64 s[24:25], s[16:17], 16
	s_add_u32 s24, s57, s24
	s_addc_u32 s25, s63, s25
	s_ashr_i32 s23, s22, 31
	s_lshl_b64 s[26:27], s[22:23], 16
	s_add_u32 s26, s66, s26
	v_mov_b32_e32 v127, 0
	s_addc_u32 s27, s67, s27
	s_and_b64 vcc, exec, s[0:1]
	v_mov_b32_e32 v126, v127
	v_mov_b32_e32 v125, v127
	v_mov_b32_e32 v124, v127
	v_mov_b32_e32 v123, v127
	v_mov_b32_e32 v122, v127
	v_mov_b32_e32 v121, v127
	v_mov_b32_e32 v120, v127
	v_mov_b32_e32 v111, v127
	v_mov_b32_e32 v110, v127
	v_mov_b32_e32 v109, v127
	v_mov_b32_e32 v108, v127
	v_mov_b32_e32 v107, v127
	v_mov_b32_e32 v106, v127
	v_mov_b32_e32 v105, v127
	v_mov_b32_e32 v104, v127
	v_mov_b32_e32 v95, v127
	v_mov_b32_e32 v94, v127
	v_mov_b32_e32 v93, v127
	v_mov_b32_e32 v92, v127
	v_mov_b32_e32 v91, v127
	v_mov_b32_e32 v90, v127
	v_mov_b32_e32 v89, v127
	v_mov_b32_e32 v88, v127
	v_mov_b32_e32 v79, v127
	v_mov_b32_e32 v78, v127
	v_mov_b32_e32 v77, v127
	v_mov_b32_e32 v76, v127
	v_mov_b32_e32 v75, v127
	v_mov_b32_e32 v74, v127
	v_mov_b32_e32 v73, v127
	v_mov_b32_e32 v72, v127
	v_mov_b32_e32 v119, v127
	v_mov_b32_e32 v118, v127
	v_mov_b32_e32 v117, v127
	v_mov_b32_e32 v116, v127
	v_mov_b32_e32 v115, v127
	v_mov_b32_e32 v114, v127
	v_mov_b32_e32 v113, v127
	v_mov_b32_e32 v112, v127
	v_mov_b32_e32 v103, v127
	v_mov_b32_e32 v102, v127
	v_mov_b32_e32 v101, v127
	v_mov_b32_e32 v100, v127
	v_mov_b32_e32 v99, v127
	v_mov_b32_e32 v98, v127
	v_mov_b32_e32 v97, v127
	v_mov_b32_e32 v96, v127
	v_mov_b32_e32 v87, v127
	v_mov_b32_e32 v86, v127
	v_mov_b32_e32 v85, v127
	v_mov_b32_e32 v84, v127
	v_mov_b32_e32 v83, v127
	v_mov_b32_e32 v82, v127
	v_mov_b32_e32 v81, v127
	v_mov_b32_e32 v80, v127
	v_mov_b32_e32 v71, v127
	v_mov_b32_e32 v70, v127
	v_mov_b32_e32 v69, v127
	v_mov_b32_e32 v68, v127
	v_mov_b32_e32 v67, v127
	v_mov_b32_e32 v66, v127
	v_mov_b32_e32 v65, v127
	v_mov_b32_e32 v64, v127
	v_mov_b32_e32 v63, v127
	v_mov_b32_e32 v62, v127
	v_mov_b32_e32 v61, v127
	v_mov_b32_e32 v60, v127
	v_mov_b32_e32 v59, v127
	v_mov_b32_e32 v58, v127
	v_mov_b32_e32 v57, v127
	v_mov_b32_e32 v56, v127
	v_mov_b32_e32 v47, v127
	v_mov_b32_e32 v46, v127
	v_mov_b32_e32 v45, v127
	v_mov_b32_e32 v44, v127
	v_mov_b32_e32 v43, v127
	v_mov_b32_e32 v42, v127
	v_mov_b32_e32 v41, v127
	v_mov_b32_e32 v40, v127
	v_mov_b32_e32 v31, v127
	v_mov_b32_e32 v30, v127
	v_mov_b32_e32 v29, v127
	v_mov_b32_e32 v28, v127
	v_mov_b32_e32 v27, v127
	v_mov_b32_e32 v26, v127
	v_mov_b32_e32 v25, v127
	v_mov_b32_e32 v24, v127
	v_mov_b32_e32 v15, v127
	v_mov_b32_e32 v14, v127
	v_mov_b32_e32 v13, v127
	v_mov_b32_e32 v12, v127
	v_mov_b32_e32 v11, v127
	v_mov_b32_e32 v10, v127
	v_mov_b32_e32 v9, v127
	v_mov_b32_e32 v8, v127
	v_mov_b32_e32 v55, v127
	v_mov_b32_e32 v54, v127
	v_mov_b32_e32 v53, v127
	v_mov_b32_e32 v52, v127
	v_mov_b32_e32 v51, v127
	v_mov_b32_e32 v50, v127
	v_mov_b32_e32 v49, v127
	v_mov_b32_e32 v48, v127
	v_mov_b32_e32 v39, v127
	v_mov_b32_e32 v38, v127
	v_mov_b32_e32 v37, v127
	v_mov_b32_e32 v36, v127
	v_mov_b32_e32 v35, v127
	v_mov_b32_e32 v34, v127
	v_mov_b32_e32 v33, v127
	v_mov_b32_e32 v32, v127
	v_mov_b32_e32 v23, v127
	v_mov_b32_e32 v22, v127
	v_mov_b32_e32 v21, v127
	v_mov_b32_e32 v20, v127
	v_mov_b32_e32 v19, v127
	v_mov_b32_e32 v18, v127
	v_mov_b32_e32 v17, v127
	v_mov_b32_e32 v16, v127
	v_mov_b32_e32 v7, v127
	v_mov_b32_e32 v6, v127
	v_mov_b32_e32 v5, v127
	v_mov_b32_e32 v4, v127
	v_mov_b32_e32 v3, v127
	v_mov_b32_e32 v2, v127
	v_mov_b32_e32 v1, v127
	v_mov_b32_e32 v0, v127
	s_cbranch_vccnz .LBB0_723
	s_and_b64 s[34:35], s[2:3], exec
	s_cselect_b32 s17, s25, s29
	s_cselect_b32 s23, s24, s28
	s_cselect_b32 s49, s27, s31
	s_cselect_b32 s50, s26, s30
	s_add_u32 s28, s28, 0x8080
	s_addc_u32 s29, s29, 0
	s_add_u32 s51, s30, 0x100
	v_mov_b32_e32 v0, 0
	s_addc_u32 s52, s31, 0
	s_mov_b32 s30, 0
	v_mov_b32_e32 v1, v0
	v_mov_b64_e32 v[2:3], 0
	v_mov_b64_e32 v[4:5], 0
	v_mov_b64_e32 v[6:7], 0
	v_mov_b64_e32 v[16:17], 0
	v_mov_b64_e32 v[18:19], 0
	v_mov_b64_e32 v[20:21], 0
	v_mov_b64_e32 v[22:23], 0
	v_mov_b64_e32 v[32:33], 0
	v_mov_b64_e32 v[34:35], 0
	v_mov_b64_e32 v[36:37], 0
	v_mov_b64_e32 v[38:39], 0
	v_mov_b64_e32 v[48:49], 0
	v_mov_b64_e32 v[50:51], 0
	v_mov_b64_e32 v[52:53], 0
	v_mov_b64_e32 v[54:55], 0
	v_mov_b64_e32 v[8:9], 0
	v_mov_b64_e32 v[10:11], 0
	v_mov_b64_e32 v[12:13], 0
	v_mov_b64_e32 v[14:15], 0
	v_mov_b64_e32 v[24:25], 0
	v_mov_b64_e32 v[26:27], 0
	v_mov_b64_e32 v[28:29], 0
	v_mov_b64_e32 v[30:31], 0
	v_mov_b64_e32 v[40:41], 0
	v_mov_b64_e32 v[42:43], 0
	v_mov_b64_e32 v[44:45], 0
	v_mov_b64_e32 v[46:47], 0
	v_mov_b64_e32 v[56:57], 0
	v_mov_b64_e32 v[58:59], 0
	v_mov_b64_e32 v[60:61], 0
	v_mov_b64_e32 v[62:63], 0
	v_mov_b64_e32 v[64:65], 0
	v_mov_b64_e32 v[66:67], 0
	v_mov_b64_e32 v[68:69], 0
	v_mov_b64_e32 v[70:71], 0
	v_mov_b64_e32 v[80:81], 0
	v_mov_b64_e32 v[82:83], 0
	v_mov_b64_e32 v[84:85], 0
	v_mov_b64_e32 v[86:87], 0
	v_mov_b64_e32 v[96:97], 0
	v_mov_b64_e32 v[98:99], 0
	v_mov_b64_e32 v[100:101], 0
	v_mov_b64_e32 v[102:103], 0
	v_mov_b64_e32 v[112:113], 0
	v_mov_b64_e32 v[114:115], 0
	v_mov_b64_e32 v[116:117], 0
	v_mov_b64_e32 v[118:119], 0
	v_mov_b64_e32 v[72:73], 0
	v_mov_b64_e32 v[74:75], 0
	v_mov_b64_e32 v[76:77], 0
	v_mov_b64_e32 v[78:79], 0
	v_mov_b64_e32 v[88:89], 0
	v_mov_b64_e32 v[90:91], 0
	v_mov_b64_e32 v[92:93], 0
	v_mov_b64_e32 v[94:95], 0
	v_mov_b64_e32 v[104:105], 0
	v_mov_b64_e32 v[106:107], 0
	v_mov_b64_e32 v[108:109], 0
	v_mov_b64_e32 v[110:111], 0
	v_mov_b64_e32 v[120:121], 0
	v_mov_b64_e32 v[122:123], 0
	v_mov_b64_e32 v[124:125], 0
	v_mov_b64_e32 v[126:127], 0

;     __device__ __forceinline__ long offA(const Unit& u) const { return (long)(u.z / zdiv) * sAo + (long)(u.z % zdiv) * sAi + (long)u.pm * BM * lda; }
;     __device__ __forceinline__ long offB(const Unit& u) const { return (long)(u.z / zdiv) * sBo + (long)(u.z % zdiv) * sBi + (long)u.pn * BM * ldb; }
; template <class Epi, bool ALIGN_EPI>
; __device__ __forceinline__ void gemm_phase(LAS unsigned char* lds, LAS unsigned char* xl, const Gemm g, const Order& S, Epi& E) {
;     ...
;         const bool has_next = S.next(ui + 1, nxt);
;         const char* nA = has_next ? (const char*)g.A + 2 * g.offA(nxt) : cA; const char* nB = has_next ? (const char*)g.Bt + 2 * g.offB(nxt) : cB;
;     ...
;         for (int a = 0; a < 2; ++a)
; #pragma unroll
;             for (int b = 0; b < 2; ++b)
; #pragma unroll
;                 for (int m = 0; m < 4; ++m)
; #pragma unroll
;                     for (int n = 0; n < 2; ++n) acc[a][b][m][n] = (f32x4){0.f, 0.f, 0.f, 0.f};
;         cur = nxt; cA = nA; cB = nB; ++ui;
.LBB0_1064:
	s_ashr_i32 s23, s22, 31
	s_lshl_b64 s[28:29], s[22:23], 19
	v_readlane_b32 s30, v253, 58
	v_readlane_b32 s31, v253, 59
	s_add_u32 s28, s30, s28
	s_addc_u32 s29, s31, s29
	s_and_b64 s[30:31], s[2:3], exec
	s_cselect_b32 s5, s29, s35
	s_cselect_b32 s23, s28, s34
	s_ashr_i32 s25, s24, 31
	s_lshl_b64 s[30:31], s[24:25], 19
	v_readlane_b32 s38, v253, 9
	v_readlane_b32 s39, v253, 10
	s_add_u32 s30, s38, s30
	s_addc_u32 s31, s39, s31
	s_and_b64 s[38:39], s[2:3], exec
	s_cselect_b32 s25, s31, s37
	s_cselect_b32 s53, s30, s36
	s_add_u32 s34, s34, 0x40080
	s_addc_u32 s35, s35, 0
	s_add_u32 s54, s36, 0x100
	v_mov_b32_e32 v0, 0
	s_addc_u32 s55, s37, 0
	s_mov_b32 s56, -2
	s_waitcnt lgkmcnt(0)
	v_mov_b32_e32 v1, v0
	v_mov_b64_e32 v[2:3], 0
	v_mov_b64_e32 v[4:5], 0
	v_mov_b64_e32 v[6:7], 0
	v_mov_b64_e32 v[16:17], 0
	v_mov_b64_e32 v[18:19], 0
	v_mov_b64_e32 v[20:21], 0
	v_mov_b64_e32 v[22:23], 0
	v_mov_b64_e32 v[32:33], 0
	v_mov_b64_e32 v[34:35], 0
	v_mov_b64_e32 v[36:37], 0
	v_mov_b64_e32 v[38:39], 0
	v_mov_b64_e32 v[48:49], 0
	v_mov_b64_e32 v[50:51], 0
	v_mov_b64_e32 v[52:53], 0
	v_mov_b64_e32 v[54:55], 0
	v_mov_b64_e32 v[8:9], 0
	v_mov_b64_e32 v[10:11], 0
	v_mov_b64_e32 v[12:13], 0
	v_mov_b64_e32 v[14:15], 0
	v_mov_b64_e32 v[24:25], 0
	v_mov_b64_e32 v[26:27], 0
	v_mov_b64_e32 v[28:29], 0
	v_mov_b64_e32 v[30:31], 0
	v_mov_b64_e32 v[40:41], 0
	v_mov_b64_e32 v[42:43], 0
	v_mov_b64_e32 v[44:45], 0
	v_mov_b64_e32 v[46:47], 0
	v_mov_b64_e32 v[56:57], 0
	v_mov_b64_e32 v[58:59], 0
	v_mov_b64_e32 v[60:61], 0
	v_mov_b64_e32 v[62:63], 0
	v_mov_b64_e32 v[68:69], 0
	v_mov_b64_e32 v[70:71], 0
	v_mov_b64_e32 v[72:73], 0
	v_mov_b64_e32 v[74:75], 0
	v_mov_b64_e32 v[92:93], 0
	v_mov_b64_e32 v[94:95], 0
	v_mov_b64_e32 v[96:97], 0
	v_mov_b64_e32 v[98:99], 0
	v_mov_b64_e32 v[116:117], 0
	v_mov_b64_e32 v[118:119], 0
	v_mov_b64_e32 v[120:121], 0
	v_mov_b64_e32 v[122:123], 0
	v_mov_b64_e32 v[140:141], 0
	v_mov_b64_e32 v[142:143], 0
	v_mov_b64_e32 v[144:145], 0
	v_mov_b64_e32 v[146:147], 0
	v_mov_b64_e32 v[80:81], 0
	v_mov_b64_e32 v[82:83], 0
	v_mov_b64_e32 v[84:85], 0
	v_mov_b64_e32 v[86:87], 0
	v_mov_b64_e32 v[104:105], 0
	v_mov_b64_e32 v[106:107], 0
	v_mov_b64_e32 v[108:109], 0
	v_mov_b64_e32 v[110:111], 0
	v_mov_b64_e32 v[128:129], 0
	v_mov_b64_e32 v[130:131], 0
	v_mov_b64_e32 v[132:133], 0
	v_mov_b64_e32 v[134:135], 0
	v_mov_b64_e32 v[152:153], 0
	v_mov_b64_e32 v[154:155], 0
	v_mov_b64_e32 v[156:157], 0
	v_mov_b64_e32 v[158:159], 0

; template <class Epi, bool ALIGN_EPI>
; __device__ __forceinline__ void gemm_phase(LAS unsigned char* lds, LAS unsigned char* xl, const Gemm g, const Order& S, Epi& E) {
;     ...
;     Unit cur, nxt; int ui = 0;
;     if (!S.next(0, cur)) return;
;     f32x4 acc[2][2][4][2];
; #pragma unroll
;     for (int a = 0; a < 2; ++a)
; #pragma unroll
;         for (int b = 0; b < 2; ++b)
; #pragma unroll
;             for (int m = 0; m < 4; ++m)
; #pragma unroll
;                 for (int n = 0; n < 2; ++n) acc[a][b][m][n] = (f32x4){0.f, 0.f, 0.f, 0.f};
.LBB0_1172:
	v_mov_b32_e32 v0, 0
	s_mov_b32 s39, 0
	s_mov_b64 s[48:49], -1
	s_mov_b64 s[50:51], 0
	v_mov_b32_e32 v1, v0
	v_mov_b64_e32 v[2:3], 0
	v_mov_b64_e32 v[4:5], 0
	v_mov_b64_e32 v[6:7], 0
	v_mov_b64_e32 v[8:9], 0
	v_mov_b64_e32 v[10:11], 0
	v_mov_b64_e32 v[16:17], 0
	v_mov_b64_e32 v[18:19], 0
	v_mov_b64_e32 v[24:25], 0
	v_mov_b64_e32 v[26:27], 0
	v_mov_b64_e32 v[32:33], 0
	v_mov_b64_e32 v[34:35], 0
	v_mov_b64_e32 v[40:41], 0
	v_mov_b64_e32 v[42:43], 0
	v_mov_b64_e32 v[48:49], 0
	v_mov_b64_e32 v[50:51], 0
	v_mov_b64_e32 v[12:13], 0
	v_mov_b64_e32 v[14:15], 0
	v_mov_b64_e32 v[20:21], 0
	v_mov_b64_e32 v[22:23], 0
	v_mov_b64_e32 v[28:29], 0
	v_mov_b64_e32 v[30:31], 0
	v_mov_b64_e32 v[36:37], 0
	v_mov_b64_e32 v[38:39], 0
	v_mov_b64_e32 v[44:45], 0
	v_mov_b64_e32 v[46:47], 0
	v_mov_b64_e32 v[52:53], 0
	v_mov_b64_e32 v[54:55], 0
	v_mov_b64_e32 v[56:57], 0
	v_mov_b64_e32 v[58:59], 0
	v_mov_b64_e32 v[60:61], 0
	v_mov_b64_e32 v[62:63], 0
	v_mov_b64_e32 v[64:65], 0
	v_mov_b64_e32 v[66:67], 0
	v_mov_b64_e32 v[68:69], 0
	v_mov_b64_e32 v[70:71], 0
	v_mov_b64_e32 v[72:73], 0
	v_mov_b64_e32 v[74:75], 0
	v_mov_b64_e32 v[80:81], 0
	v_mov_b64_e32 v[82:83], 0
	v_mov_b64_e32 v[88:89], 0
	v_mov_b64_e32 v[90:91], 0
	v_mov_b64_e32 v[96:97], 0
	v_mov_b64_e32 v[98:99], 0
	v_mov_b64_e32 v[104:105], 0
	v_mov_b64_e32 v[106:107], 0
	v_mov_b64_e32 v[112:113], 0
	v_mov_b64_e32 v[114:115], 0
	v_mov_b64_e32 v[76:77], 0
	v_mov_b64_e32 v[78:79], 0
	v_mov_b64_e32 v[84:85], 0
	v_mov_b64_e32 v[86:87], 0
	v_mov_b64_e32 v[92:93], 0
	v_mov_b64_e32 v[94:95], 0
	v_mov_b64_e32 v[100:101], 0
	v_mov_b64_e32 v[102:103], 0
	v_mov_b64_e32 v[108:109], 0
	v_mov_b64_e32 v[110:111], 0
	v_mov_b64_e32 v[116:117], 0
	v_mov_b64_e32 v[118:119], 0
	v_mov_b64_e32 v[120:121], 0
	v_mov_b64_e32 v[122:123], 0
	v_mov_b64_e32 v[124:125], 0
	v_mov_b64_e32 v[126:127], 0

; template <class Epi, bool ALIGN_EPI>
; __device__ __forceinline__ void gemm_phase(LAS unsigned char* lds, LAS unsigned char* xl, const Gemm g, const Order& S, Epi& E) {
;     ...
;     Unit cur, nxt; int ui = 0;
;     if (!S.next(0, cur)) return;
;     f32x4 acc[2][2][4][2];
; #pragma unroll
;     for (int a = 0; a < 2; ++a)
; #pragma unroll
;         for (int b = 0; b < 2; ++b)
; #pragma unroll
;             for (int m = 0; m < 4; ++m)
; #pragma unroll
;                 for (int n = 0; n < 2; ++n) acc[a][b][m][n] = (f32x4){0.f, 0.f, 0.f, 0.f};
.LBB0_1192:
	v_mov_b32_e32 v0, 0
	s_mov_b32 s35, 0
	s_mov_b64 s[44:45], -1
	s_mov_b64 s[46:47], 0
	v_mov_b32_e32 v1, v0
	v_mov_b64_e32 v[2:3], 0
	v_mov_b64_e32 v[4:5], 0
	v_mov_b64_e32 v[6:7], 0
	v_mov_b64_e32 v[8:9], 0
	v_mov_b64_e32 v[10:11], 0
	v_mov_b64_e32 v[12:13], 0
	v_mov_b64_e32 v[14:15], 0
	v_mov_b64_e32 v[24:25], 0
	v_mov_b64_e32 v[26:27], 0
	v_mov_b64_e32 v[28:29], 0
	v_mov_b64_e32 v[30:31], 0
	v_mov_b64_e32 v[40:41], 0
	v_mov_b64_e32 v[42:43], 0
	v_mov_b64_e32 v[44:45], 0
	v_mov_b64_e32 v[46:47], 0
	v_mov_b64_e32 v[16:17], 0
	v_mov_b64_e32 v[18:19], 0
	v_mov_b64_e32 v[20:21], 0
	v_mov_b64_e32 v[22:23], 0
	v_mov_b64_e32 v[32:33], 0
	v_mov_b64_e32 v[34:35], 0
	v_mov_b64_e32 v[36:37], 0
	v_mov_b64_e32 v[38:39], 0
	v_mov_b64_e32 v[48:49], 0
	v_mov_b64_e32 v[50:51], 0
	v_mov_b64_e32 v[52:53], 0
	v_mov_b64_e32 v[54:55], 0
	v_mov_b64_e32 v[56:57], 0
	v_mov_b64_e32 v[58:59], 0
	v_mov_b64_e32 v[60:61], 0
	v_mov_b64_e32 v[62:63], 0
	v_mov_b64_e32 v[64:65], 0
	v_mov_b64_e32 v[66:67], 0
	v_mov_b64_e32 v[68:69], 0
	v_mov_b64_e32 v[70:71], 0
	v_mov_b64_e32 v[72:73], 0
	v_mov_b64_e32 v[74:75], 0
	v_mov_b64_e32 v[76:77], 0
	v_mov_b64_e32 v[78:79], 0
	v_mov_b64_e32 v[88:89], 0
	v_mov_b64_e32 v[90:91], 0
	v_mov_b64_e32 v[92:93], 0
	v_mov_b64_e32 v[94:95], 0
	v_mov_b64_e32 v[104:105], 0
	v_mov_b64_e32 v[106:107], 0
	v_mov_b64_e32 v[108:109], 0
	v_mov_b64_e32 v[110:111], 0
	v_mov_b64_e32 v[80:81], 0
	v_mov_b64_e32 v[82:83], 0
	v_mov_b64_e32 v[84:85], 0
	v_mov_b64_e32 v[86:87], 0
	v_mov_b64_e32 v[96:97], 0
	v_mov_b64_e32 v[98:99], 0
	v_mov_b64_e32 v[100:101], 0
	v_mov_b64_e32 v[102:103], 0
	v_mov_b64_e32 v[112:113], 0
	v_mov_b64_e32 v[114:115], 0
	v_mov_b64_e32 v[116:117], 0
	v_mov_b64_e32 v[118:119], 0
	v_mov_b64_e32 v[120:121], 0
	v_mov_b64_e32 v[122:123], 0
	v_mov_b64_e32 v[124:125], 0
	v_mov_b64_e32 v[126:127], 0

; #define LAS __attribute__((address_space(3)))
;     __device__ __forceinline__ long offA(const Unit& u) const { return (long)(u.z / zdiv) * sAo + (long)(u.z % zdiv) * sAi + (long)u.pm * BM * lda; }
;     __device__ __forceinline__ long offB(const Unit& u) const { return (long)(u.z / zdiv) * sBo + (long)(u.z % zdiv) * sBi + (long)u.pn * BM * ldb; }
; template <class Epi, bool ALIGN_EPI>
; __device__ __forceinline__ void gemm_phase(LAS unsigned char* lds, LAS unsigned char* xl, const Gemm g, const Order& S, Epi& E) {
;     ...
;         const bool has_next = S.next(ui + 1, nxt);
;         const char* nA = has_next ? (const char*)g.A + 2 * g.offA(nxt) : cA; const char* nB = has_next ? (const char*)g.Bt + 2 * g.offB(nxt) : cB;
;         for (int t = 0; t < nt; t += 2) {
;             const bool last = (t == nt - 2);
;             const char* a1 = cA + (size_t)(t + 1) * kstep;
;             const char* a2 = last ? nA : cA + (size_t)(t + 2) * kstep; const char* b2 = last ? nB : cB + (size_t)(t + 2) * kstep;
;             const char* a3 = a2 + kstep; const char* b3 = b2 + kstep;
;             if constexpr (Epi::PSLDS) { if (last) {
;                 const char* psrc = (const char*)(E.PS + (size_t)((cur.z / g.zdiv) * g.psz + cur.pm) * (BM * 16)) + tid * 16;
; #pragma unroll
;                 for (int _i = 0; _i < 2; ++_i) __builtin_amdgcn_global_load_lds((const unsigned*)(psrc + _i * 8192), (LAS unsigned*)(xl + 8192 + ldsw + _i * 8192), 16, 0, 0); } }
;     ...
;         for (int a = 0; a < 2; ++a)
; #pragma unroll
;             for (int b = 0; b < 2; ++b)
; #pragma unroll
;                 for (int m = 0; m < 4; ++m)
; #pragma unroll
;                     for (int n = 0; n < 2; ++n) acc[a][b][m][n] = (f32x4){0.f, 0.f, 0.f, 0.f};
;         cur = nxt; cA = nA; cB = nB; ++ui;
.LBB0_1272:
	s_ashr_i32 s29, s67, 31
	s_lshr_b32 s29, s29, 30
	s_add_i32 s29, s67, s29
	s_ashr_i32 s38, s29, 2
	s_lshl_b32 s29, s38, 4
	s_add_i32 s44, s29, s36
	s_ashr_i32 s45, s44, 31
	s_lshl_b64 s[44:45], s[44:45], 14
	s_add_u32 s40, s40, 0x40080
	s_addc_u32 s41, s41, 0
	v_lshl_add_u64 v[150:151], v[138:139], 0, s[44:45]
	s_add_u32 s29, s42, 0x100
	v_mov_b32_e32 v0, 0
	v_lshl_add_u64 v[152:153], v[150:151], 0, s[16:17]
	s_addc_u32 s31, s43, 0
	s_mov_b32 s39, -2
	v_mov_b32_e32 v1, v0
	v_mov_b64_e32 v[2:3], 0
	v_mov_b64_e32 v[4:5], 0
	v_mov_b64_e32 v[6:7], 0
	v_mov_b64_e32 v[16:17], 0
	v_mov_b64_e32 v[18:19], 0
	v_mov_b64_e32 v[20:21], 0
	v_mov_b64_e32 v[22:23], 0
	v_mov_b64_e32 v[32:33], 0
	v_mov_b64_e32 v[34:35], 0
	v_mov_b64_e32 v[36:37], 0
	v_mov_b64_e32 v[38:39], 0
	v_mov_b64_e32 v[48:49], 0
	v_mov_b64_e32 v[50:51], 0
	v_mov_b64_e32 v[52:53], 0
	v_mov_b64_e32 v[54:55], 0
	v_mov_b64_e32 v[8:9], 0
	v_mov_b64_e32 v[10:11], 0
	v_mov_b64_e32 v[12:13], 0
	v_mov_b64_e32 v[14:15], 0
	v_mov_b64_e32 v[24:25], 0
	v_mov_b64_e32 v[26:27], 0
	v_mov_b64_e32 v[28:29], 0
	v_mov_b64_e32 v[30:31], 0
	v_mov_b64_e32 v[40:41], 0
	v_mov_b64_e32 v[42:43], 0
	v_mov_b64_e32 v[44:45], 0
	v_mov_b64_e32 v[46:47], 0
	v_mov_b64_e32 v[56:57], 0
	v_mov_b64_e32 v[58:59], 0
	v_mov_b64_e32 v[60:61], 0
	v_mov_b64_e32 v[62:63], 0
	v_mov_b64_e32 v[64:65], 0
	v_mov_b64_e32 v[66:67], 0
	v_mov_b64_e32 v[68:69], 0
	v_mov_b64_e32 v[70:71], 0
	v_mov_b64_e32 v[80:81], 0
	v_mov_b64_e32 v[82:83], 0
	v_mov_b64_e32 v[84:85], 0
	v_mov_b64_e32 v[86:87], 0
	v_mov_b64_e32 v[96:97], 0
	v_mov_b64_e32 v[98:99], 0
	v_mov_b64_e32 v[100:101], 0
	v_mov_b64_e32 v[102:103], 0
	v_mov_b64_e32 v[112:113], 0
	v_mov_b64_e32 v[114:115], 0
	v_mov_b64_e32 v[116:117], 0
	v_mov_b64_e32 v[118:119], 0
	v_mov_b64_e32 v[72:73], 0
	v_mov_b64_e32 v[74:75], 0
	v_mov_b64_e32 v[76:77], 0
	v_mov_b64_e32 v[78:79], 0
	v_mov_b64_e32 v[88:89], 0
	v_mov_b64_e32 v[90:91], 0
	v_mov_b64_e32 v[92:93], 0
	v_mov_b64_e32 v[94:95], 0
	v_mov_b64_e32 v[104:105], 0
	v_mov_b64_e32 v[106:107], 0
	v_mov_b64_e32 v[108:109], 0
	v_mov_b64_e32 v[110:111], 0
	v_mov_b64_e32 v[120:121], 0
	v_mov_b64_e32 v[122:123], 0
	v_mov_b64_e32 v[124:125], 0
	v_mov_b64_e32 v[126:127], 0
	s_branch .LBB0_1274

;     __device__ __forceinline__ long offA(const Unit& u) const { return (long)(u.z / zdiv) * sAo + (long)(u.z % zdiv) * sAi + (long)u.pm * BM * lda; }
;     __device__ __forceinline__ long offB(const Unit& u) const { return (long)(u.z / zdiv) * sBo + (long)(u.z % zdiv) * sBi + (long)u.pn * BM * ldb; }
; template <class Epi, bool ALIGN_EPI>
; __device__ __forceinline__ void gemm_phase(LAS unsigned char* lds, LAS unsigned char* xl, const Gemm g, const Order& S, Epi& E) {
;     ...
;         const bool has_next = S.next(ui + 1, nxt);
;         const char* nA = has_next ? (const char*)g.A + 2 * g.offA(nxt) : cA; const char* nB = has_next ? (const char*)g.Bt + 2 * g.offB(nxt) : cB;
;     ...
;         for (int a = 0; a < 2; ++a)
; #pragma unroll
;             for (int b = 0; b < 2; ++b)
; #pragma unroll
;                 for (int m = 0; m < 4; ++m)
; #pragma unroll
;                     for (int n = 0; n < 2; ++n) acc[a][b][m][n] = (f32x4){0.f, 0.f, 0.f, 0.f};
;         cur = nxt; cA = nA; cB = nB; ++ui;
.LBB0_1387:
	s_add_u32 s30, s30, 0x40080
	s_addc_u32 s31, s31, 0
	s_add_u32 s17, s34, 0x100
	v_mov_b32_e32 v0, 0
	s_addc_u32 s19, s35, 0
	s_mov_b32 s21, -2
	v_mov_b32_e32 v1, v0
	v_mov_b64_e32 v[2:3], 0
	v_mov_b64_e32 v[4:5], 0
	v_mov_b64_e32 v[6:7], 0
	v_mov_b64_e32 v[16:17], 0
	v_mov_b64_e32 v[18:19], 0
	v_mov_b64_e32 v[20:21], 0
	v_mov_b64_e32 v[22:23], 0
	v_mov_b64_e32 v[32:33], 0
	v_mov_b64_e32 v[34:35], 0
	v_mov_b64_e32 v[36:37], 0
	v_mov_b64_e32 v[38:39], 0
	v_mov_b64_e32 v[48:49], 0
	v_mov_b64_e32 v[50:51], 0
	v_mov_b64_e32 v[52:53], 0
	v_mov_b64_e32 v[54:55], 0
	v_mov_b64_e32 v[8:9], 0
	v_mov_b64_e32 v[10:11], 0
	v_mov_b64_e32 v[12:13], 0
	v_mov_b64_e32 v[14:15], 0
	v_mov_b64_e32 v[24:25], 0
	v_mov_b64_e32 v[26:27], 0
	v_mov_b64_e32 v[28:29], 0
	v_mov_b64_e32 v[30:31], 0
	v_mov_b64_e32 v[40:41], 0
	v_mov_b64_e32 v[42:43], 0
	v_mov_b64_e32 v[44:45], 0
	v_mov_b64_e32 v[46:47], 0
	v_mov_b64_e32 v[56:57], 0
	v_mov_b64_e32 v[58:59], 0
	v_mov_b64_e32 v[60:61], 0
	v_mov_b64_e32 v[62:63], 0
	v_mov_b64_e32 v[64:65], 0
	v_mov_b64_e32 v[66:67], 0
	v_mov_b64_e32 v[68:69], 0
	v_mov_b64_e32 v[70:71], 0
	v_mov_b64_e32 v[80:81], 0
	v_mov_b64_e32 v[82:83], 0
	v_mov_b64_e32 v[84:85], 0
	v_mov_b64_e32 v[86:87], 0
	v_mov_b64_e32 v[96:97], 0
	v_mov_b64_e32 v[98:99], 0
	v_mov_b64_e32 v[100:101], 0
	v_mov_b64_e32 v[102:103], 0
	v_mov_b64_e32 v[116:117], 0
	v_mov_b64_e32 v[118:119], 0
	v_mov_b64_e32 v[124:125], 0
	v_mov_b64_e32 v[126:127], 0
	v_mov_b64_e32 v[72:73], 0
	v_mov_b64_e32 v[74:75], 0
	v_mov_b64_e32 v[76:77], 0
	v_mov_b64_e32 v[78:79], 0
	v_mov_b64_e32 v[88:89], 0
	v_mov_b64_e32 v[90:91], 0
	v_mov_b64_e32 v[92:93], 0
	v_mov_b64_e32 v[94:95], 0
	v_mov_b64_e32 v[104:105], 0
	v_mov_b64_e32 v[106:107], 0
	v_mov_b64_e32 v[112:113], 0
	v_mov_b64_e32 v[114:115], 0
	v_mov_b64_e32 v[132:133], 0
	v_mov_b64_e32 v[134:135], 0
	v_mov_b64_e32 v[136:137], 0
	v_mov_b64_e32 v[138:139], 0

; #define LAS __attribute__((address_space(3)))
;     __device__ __forceinline__ long offA(const Unit& u) const { return (long)(u.z / zdiv) * sAo + (long)(u.z % zdiv) * sAi + (long)u.pm * BM * lda; }
;     __device__ __forceinline__ long offB(const Unit& u) const { return (long)(u.z / zdiv) * sBo + (long)(u.z % zdiv) * sBi + (long)u.pn * BM * ldb; }
; template <class Epi, bool ALIGN_EPI>
; __device__ __forceinline__ void gemm_phase(LAS unsigned char* lds, LAS unsigned char* xl, const Gemm g, const Order& S, Epi& E) {
;     ...
;         const bool has_next = S.next(ui + 1, nxt);
;         const char* nA = has_next ? (const char*)g.A + 2 * g.offA(nxt) : cA; const char* nB = has_next ? (const char*)g.Bt + 2 * g.offB(nxt) : cB;
;         for (int t = 0; t < nt; t += 2) {
;             const bool last = (t == nt - 2);
;             const char* a1 = cA + (size_t)(t + 1) * kstep;
;             const char* a2 = last ? nA : cA + (size_t)(t + 2) * kstep; const char* b2 = last ? nB : cB + (size_t)(t + 2) * kstep;
;             const char* a3 = a2 + kstep; const char* b3 = b2 + kstep;
;             if constexpr (Epi::PSLDS) { if (last) {
;                 const char* psrc = (const char*)(E.PS + (size_t)((cur.z / g.zdiv) * g.psz + cur.pm) * (BM * 16)) + tid * 16;
; #pragma unroll
;                 for (int _i = 0; _i < 2; ++_i) __builtin_amdgcn_global_load_lds((const unsigned*)(psrc + _i * 8192), (LAS unsigned*)(xl + 8192 + ldsw + _i * 8192), 16, 0, 0); } }
;     ...
;         for (int a = 0; a < 2; ++a)
; #pragma unroll
;             for (int b = 0; b < 2; ++b)
; #pragma unroll
;                 for (int m = 0; m < 4; ++m)
; #pragma unroll
;                     for (int n = 0; n < 2; ++n) acc[a][b][m][n] = (f32x4){0.f, 0.f, 0.f, 0.f};
;         cur = nxt; cA = nA; cB = nB; ++ui;
.LBB0_1474:
	s_ashr_i32 s21, s20, 31
	s_lshl_b64 s[24:25], s[20:21], 19
	v_readlane_b32 s28, v253, 21
	v_readlane_b32 s29, v253, 22
	s_add_u32 s24, s28, s24
	s_addc_u32 s25, s29, s25
	s_and_b64 s[28:29], s[0:1], exec
	s_cselect_b32 s21, s25, s5
	s_cselect_b32 s52, s24, s4
	s_ashr_i32 s23, s22, 31
	s_lshl_b64 s[28:29], s[22:23], 19
	v_readlane_b32 s3, v253, 17
	s_add_u32 s28, s3, s28
	v_readlane_b32 s3, v253, 18
	s_addc_u32 s29, s3, s29
	s_and_b64 s[34:35], s[0:1], exec
	s_cselect_b32 s23, s29, s31
	s_cselect_b32 s53, s28, s30
	s_ashr_i32 s3, s2, 31
	s_lshl_b64 s[34:35], s[2:3], 14
	s_add_u32 s4, s4, 0x40080
	s_addc_u32 s5, s5, 0
	v_lshl_add_u64 v[146:147], v[136:137], 0, s[34:35]
	s_add_u32 s3, s30, 0x100
	v_mov_b32_e32 v0, 0
	v_lshl_add_u64 v[148:149], v[146:147], 0, s[14:15]
	s_addc_u32 s54, s31, 0
	s_mov_b32 s55, -2
	v_mov_b32_e32 v1, v0
	v_mov_b64_e32 v[2:3], 0
	v_mov_b64_e32 v[4:5], 0
	v_mov_b64_e32 v[6:7], 0
	v_mov_b64_e32 v[16:17], 0
	v_mov_b64_e32 v[18:19], 0
	v_mov_b64_e32 v[20:21], 0
	v_mov_b64_e32 v[22:23], 0
	v_mov_b64_e32 v[32:33], 0
	v_mov_b64_e32 v[34:35], 0
	v_mov_b64_e32 v[36:37], 0
	v_mov_b64_e32 v[38:39], 0
	v_mov_b64_e32 v[48:49], 0
	v_mov_b64_e32 v[50:51], 0
	v_mov_b64_e32 v[52:53], 0
	v_mov_b64_e32 v[54:55], 0
	v_mov_b64_e32 v[8:9], 0
	v_mov_b64_e32 v[10:11], 0
	v_mov_b64_e32 v[12:13], 0
	v_mov_b64_e32 v[14:15], 0
	v_mov_b64_e32 v[24:25], 0
	v_mov_b64_e32 v[26:27], 0
	v_mov_b64_e32 v[28:29], 0
	v_mov_b64_e32 v[30:31], 0
	v_mov_b64_e32 v[40:41], 0
	v_mov_b64_e32 v[42:43], 0
	v_mov_b64_e32 v[44:45], 0
	v_mov_b64_e32 v[46:47], 0
	v_mov_b64_e32 v[56:57], 0
	v_mov_b64_e32 v[58:59], 0
	v_mov_b64_e32 v[60:61], 0
	v_mov_b64_e32 v[62:63], 0
	v_mov_b64_e32 v[64:65], 0
	v_mov_b64_e32 v[66:67], 0
	v_mov_b64_e32 v[68:69], 0
	v_mov_b64_e32 v[70:71], 0
	v_mov_b64_e32 v[80:81], 0
	v_mov_b64_e32 v[82:83], 0
	v_mov_b64_e32 v[84:85], 0
	v_mov_b64_e32 v[86:87], 0
	v_mov_b64_e32 v[96:97], 0
	v_mov_b64_e32 v[98:99], 0
	v_mov_b64_e32 v[100:101], 0
	v_mov_b64_e32 v[102:103], 0
	v_mov_b64_e32 v[112:113], 0
	v_mov_b64_e32 v[114:115], 0
	v_mov_b64_e32 v[116:117], 0
	v_mov_b64_e32 v[118:119], 0
	v_mov_b64_e32 v[72:73], 0
	v_mov_b64_e32 v[74:75], 0
	v_mov_b64_e32 v[76:77], 0
	v_mov_b64_e32 v[78:79], 0
	v_mov_b64_e32 v[88:89], 0
	v_mov_b64_e32 v[90:91], 0
	v_mov_b64_e32 v[92:93], 0
	v_mov_b64_e32 v[94:95], 0
	v_mov_b64_e32 v[104:105], 0
	v_mov_b64_e32 v[106:107], 0
	v_mov_b64_e32 v[108:109], 0
	v_mov_b64_e32 v[110:111], 0
	v_mov_b64_e32 v[120:121], 0
	v_mov_b64_e32 v[122:123], 0
	v_mov_b64_e32 v[124:125], 0
	v_mov_b64_e32 v[126:127], 0
	s_branch .LBB0_1476

;     __device__ __forceinline__ long offA(const Unit& u) const { return (long)(u.z / zdiv) * sAo + (long)(u.z % zdiv) * sAi + (long)u.pm * BM * lda; }
;     __device__ __forceinline__ long offB(const Unit& u) const { return (long)(u.z / zdiv) * sBo + (long)(u.z % zdiv) * sBi + (long)u.pn * BM * ldb; }
; template <class Epi, bool ALIGN_EPI>
; __device__ __forceinline__ void gemm_phase(LAS unsigned char* lds, LAS unsigned char* xl, const Gemm g, const Order& S, Epi& E) {
;     ...
;         const bool has_next = S.next(ui + 1, nxt);
;         const char* nA = has_next ? (const char*)g.A + 2 * g.offA(nxt) : cA; const char* nB = has_next ? (const char*)g.Bt + 2 * g.offB(nxt) : cB;
;     ...
;         for (int a = 0; a < 2; ++a)
; #pragma unroll
;             for (int b = 0; b < 2; ++b)
; #pragma unroll
;                 for (int m = 0; m < 4; ++m)
; #pragma unroll
;                     for (int n = 0; n < 2; ++n) acc[a][b][m][n] = (f32x4){0.f, 0.f, 0.f, 0.f};
;         cur = nxt; cA = nA; cB = nB; ++ui;
.LBB0_1557:
	s_add_u32 s18, s18, 0xb0080
	s_addc_u32 s19, s19, 0
	s_add_u32 s45, s20, 0x100
	v_mov_b32_e32 v0, 0
	s_addc_u32 s47, s21, 0
	s_mov_b32 s48, -2
	v_mov_b32_e32 v1, v0
	v_mov_b64_e32 v[2:3], 0
	v_mov_b64_e32 v[4:5], 0
	v_mov_b64_e32 v[6:7], 0
	v_mov_b64_e32 v[16:17], 0
	v_mov_b64_e32 v[18:19], 0
	v_mov_b64_e32 v[20:21], 0
	v_mov_b64_e32 v[22:23], 0
	v_mov_b64_e32 v[32:33], 0
	v_mov_b64_e32 v[34:35], 0
	v_mov_b64_e32 v[36:37], 0
	v_mov_b64_e32 v[38:39], 0
	v_mov_b64_e32 v[48:49], 0
	v_mov_b64_e32 v[50:51], 0
	v_mov_b64_e32 v[52:53], 0
	v_mov_b64_e32 v[54:55], 0
	v_mov_b64_e32 v[8:9], 0
	v_mov_b64_e32 v[10:11], 0
	v_mov_b64_e32 v[12:13], 0
	v_mov_b64_e32 v[14:15], 0
	v_mov_b64_e32 v[24:25], 0
	v_mov_b64_e32 v[26:27], 0
	v_mov_b64_e32 v[28:29], 0
	v_mov_b64_e32 v[30:31], 0
	v_mov_b64_e32 v[40:41], 0
	v_mov_b64_e32 v[42:43], 0
	v_mov_b64_e32 v[44:45], 0
	v_mov_b64_e32 v[46:47], 0
	v_mov_b64_e32 v[56:57], 0
	v_mov_b64_e32 v[58:59], 0
	v_mov_b64_e32 v[60:61], 0
	v_mov_b64_e32 v[62:63], 0
	v_mov_b64_e32 v[64:65], 0
	v_mov_b64_e32 v[66:67], 0
	v_mov_b64_e32 v[68:69], 0
	v_mov_b64_e32 v[70:71], 0
	v_mov_b64_e32 v[80:81], 0
	v_mov_b64_e32 v[82:83], 0
	v_mov_b64_e32 v[84:85], 0
	v_mov_b64_e32 v[86:87], 0
	v_mov_b64_e32 v[96:97], 0
	v_mov_b64_e32 v[98:99], 0
	v_mov_b64_e32 v[100:101], 0
	v_mov_b64_e32 v[102:103], 0
	v_mov_b64_e32 v[112:113], 0
	v_mov_b64_e32 v[114:115], 0
	v_mov_b64_e32 v[116:117], 0
	v_mov_b64_e32 v[118:119], 0
	v_mov_b64_e32 v[72:73], 0
	v_mov_b64_e32 v[74:75], 0
	v_mov_b64_e32 v[76:77], 0
	v_mov_b64_e32 v[78:79], 0
	v_mov_b64_e32 v[88:89], 0
	v_mov_b64_e32 v[90:91], 0
	v_mov_b64_e32 v[92:93], 0
	v_mov_b64_e32 v[94:95], 0
	v_mov_b64_e32 v[104:105], 0
	v_mov_b64_e32 v[106:107], 0
	v_mov_b64_e32 v[108:109], 0
	v_mov_b64_e32 v[110:111], 0
	v_mov_b64_e32 v[132:133], 0
	v_mov_b64_e32 v[134:135], 0
	v_mov_b64_e32 v[136:137], 0
	v_mov_b64_e32 v[138:139], 0

; #define LAS __attribute__((address_space(3)))
;     __device__ __forceinline__ long offA(const Unit& u) const { return (long)(u.z / zdiv) * sAo + (long)(u.z % zdiv) * sAi + (long)u.pm * BM * lda; }
;     __device__ __forceinline__ long offB(const Unit& u) const { return (long)(u.z / zdiv) * sBo + (long)(u.z % zdiv) * sBi + (long)u.pn * BM * ldb; }
; template <class Epi, bool ALIGN_EPI>
; __device__ __forceinline__ void gemm_phase(LAS unsigned char* lds, LAS unsigned char* xl, const Gemm g, const Order& S, Epi& E) {
;     ...
;         const bool has_next = S.next(ui + 1, nxt);
;         const char* nA = has_next ? (const char*)g.A + 2 * g.offA(nxt) : cA; const char* nB = has_next ? (const char*)g.Bt + 2 * g.offB(nxt) : cB;
;         for (int t = 0; t < nt; t += 2) {
;             const bool last = (t == nt - 2);
;             const char* a1 = cA + (size_t)(t + 1) * kstep;
;             const char* a2 = last ? nA : cA + (size_t)(t + 2) * kstep; const char* b2 = last ? nB : cB + (size_t)(t + 2) * kstep;
;             const char* a3 = a2 + kstep; const char* b3 = b2 + kstep;
;             if constexpr (Epi::PSLDS) { if (last) {
;                 const char* psrc = (const char*)(E.PS + (size_t)((cur.z / g.zdiv) * g.psz + cur.pm) * (BM * 16)) + tid * 16;
; #pragma unroll
;                 for (int _i = 0; _i < 2; ++_i) __builtin_amdgcn_global_load_lds((const unsigned*)(psrc + _i * 8192), (LAS unsigned*)(xl + 8192 + ldsw + _i * 8192), 16, 0, 0); } }
;     ...
;         for (int a = 0; a < 2; ++a)
; #pragma unroll
;             for (int b = 0; b < 2; ++b)
; #pragma unroll
;                 for (int m = 0; m < 4; ++m)
; #pragma unroll
;                     for (int n = 0; n < 2; ++n) acc[a][b][m][n] = (f32x4){0.f, 0.f, 0.f, 0.f};
;         cur = nxt; cA = nA; cB = nB; ++ui;
.LBB0_1644:
	s_ashr_i32 s21, s20, 31
	s_lshl_b64 s[24:25], s[20:21], 19
	v_readlane_b32 s28, v253, 21
	v_readlane_b32 s29, v253, 22
	s_add_u32 s24, s28, s24
	s_addc_u32 s25, s29, s25
	s_and_b64 s[28:29], s[0:1], exec
	s_cselect_b32 s21, s25, s5
	s_cselect_b32 s52, s24, s4
	s_ashr_i32 s23, s22, 31
	s_lshl_b64 s[28:29], s[22:23], 19
	v_readlane_b32 s34, v253, 11
	v_readlane_b32 s35, v253, 12
	s_add_u32 s28, s34, s28
	s_addc_u32 s29, s35, s29
	s_and_b64 s[34:35], s[0:1], exec
	s_cselect_b32 s23, s29, s31
	s_cselect_b32 s53, s28, s30
	s_ashr_i32 s3, s2, 31
	s_lshl_b64 s[34:35], s[2:3], 14
	s_add_u32 s4, s4, 0x40080
	s_addc_u32 s5, s5, 0
	v_lshl_add_u64 v[146:147], v[136:137], 0, s[34:35]
	s_add_u32 s3, s30, 0x100
	v_mov_b32_e32 v0, 0
	v_lshl_add_u64 v[148:149], v[146:147], 0, s[14:15]
	s_addc_u32 s54, s31, 0
	s_mov_b32 s55, -2
	v_mov_b32_e32 v1, v0
	v_mov_b64_e32 v[2:3], 0
	v_mov_b64_e32 v[4:5], 0
	v_mov_b64_e32 v[6:7], 0
	v_mov_b64_e32 v[8:9], 0
	v_mov_b64_e32 v[10:11], 0
	v_mov_b64_e32 v[16:17], 0
	v_mov_b64_e32 v[18:19], 0
	v_mov_b64_e32 v[24:25], 0
	v_mov_b64_e32 v[26:27], 0
	v_mov_b64_e32 v[32:33], 0
	v_mov_b64_e32 v[34:35], 0
	v_mov_b64_e32 v[40:41], 0
	v_mov_b64_e32 v[42:43], 0
	v_mov_b64_e32 v[48:49], 0
	v_mov_b64_e32 v[50:51], 0
	v_mov_b64_e32 v[12:13], 0
	v_mov_b64_e32 v[14:15], 0
	v_mov_b64_e32 v[20:21], 0
	v_mov_b64_e32 v[22:23], 0
	v_mov_b64_e32 v[28:29], 0
	v_mov_b64_e32 v[30:31], 0
	v_mov_b64_e32 v[36:37], 0
	v_mov_b64_e32 v[38:39], 0
	v_mov_b64_e32 v[44:45], 0
	v_mov_b64_e32 v[46:47], 0
	v_mov_b64_e32 v[52:53], 0
	v_mov_b64_e32 v[54:55], 0
	v_mov_b64_e32 v[56:57], 0
	v_mov_b64_e32 v[58:59], 0
	v_mov_b64_e32 v[60:61], 0
	v_mov_b64_e32 v[62:63], 0
	v_mov_b64_e32 v[64:65], 0
	v_mov_b64_e32 v[66:67], 0
	v_mov_b64_e32 v[68:69], 0
	v_mov_b64_e32 v[70:71], 0
	v_mov_b64_e32 v[72:73], 0
	v_mov_b64_e32 v[74:75], 0
	v_mov_b64_e32 v[80:81], 0
	v_mov_b64_e32 v[82:83], 0
	v_mov_b64_e32 v[88:89], 0
	v_mov_b64_e32 v[90:91], 0
	v_mov_b64_e32 v[96:97], 0
	v_mov_b64_e32 v[98:99], 0
	v_mov_b64_e32 v[104:105], 0
	v_mov_b64_e32 v[106:107], 0
	v_mov_b64_e32 v[112:113], 0
	v_mov_b64_e32 v[114:115], 0
	v_mov_b64_e32 v[76:77], 0
	v_mov_b64_e32 v[78:79], 0
	v_mov_b64_e32 v[84:85], 0
	v_mov_b64_e32 v[86:87], 0
	v_mov_b64_e32 v[92:93], 0
	v_mov_b64_e32 v[94:95], 0
	v_mov_b64_e32 v[100:101], 0
	v_mov_b64_e32 v[102:103], 0
	v_mov_b64_e32 v[108:109], 0
	v_mov_b64_e32 v[110:111], 0
	v_mov_b64_e32 v[116:117], 0
	v_mov_b64_e32 v[118:119], 0
	v_mov_b64_e32 v[120:121], 0
	v_mov_b64_e32 v[122:123], 0
	v_mov_b64_e32 v[124:125], 0
	v_mov_b64_e32 v[126:127], 0
	s_branch .LBB0_1646

; #define LAS __attribute__((address_space(3)))
; __device__ __forceinline__ float frcp(float x) { return __builtin_amdgcn_rcpf(x); }
; #define HG_ISSUE(t0n) do { _Pragma("unroll") for (int i = 0; i < 16; ++i) { const int tk = (t0n) + (dir ? 63 - (i0 + i) : (i0 + i)); const bf16_t* pr = Pb + (size_t)tk * HGP + h * 128 + dcol; \
;         rq[i] = pr[0]; rf[i] = pr[1024 * (1 + dir)]; rv[i] = pr[3072]; } } while (0)
; __device__ __forceinline__ void hgrn_chain(LAS unsigned char* lds, int cid, bf16_t* P1, const float* hg_lb, bf16_t* Ob, int ldo, int ocbase, int ocdir) {
;     ...
;     __syncthreads();
;     for (int e = tid; e < 128 * HLD / 2; e += 512) ((LAS unsigned*)ST)[e] = 0u;
;     const int dcol = tid & 127, qtr = tid >> 7, i0 = qtr * 16;
;     const float lbv = frcp(1.0f + __expf(hg_lb[h * 128 + dcol] - hg_lb[1024 + h * 128 + dcol]));
;     f32x4 st[8];
; #pragma unroll
;     for (int i = 0; i < 8; ++i) st[i] = (f32x4){0.f, 0.f, 0.f, 0.f};
;     bf16_t* Pb = P1 + (size_t)b * SEQ * HGP;
;     __syncthreads();
;     unsigned short rq[16], rf[16], rv[16];
;     ...
;     HG_ISSUE((dir ? 63 : 0) * 64);
.LBB0_1713:
	v_add_u32_e32 v1, 0x200, v1
	v_cmp_lt_u32_e32 vcc, s38, v1
	ds_write_b32 v0, v43
	s_or_b64 s[34:35], vcc, s[34:35]
	v_add_u32_e32 v0, 0x800, v0
	s_andn2_b64 exec, exec, s[34:35]
	s_cbranch_execnz .LBB0_1713
	s_or_b64 exec, exec, s[34:35]
	s_lshl_b32 s30, s41, 6
	s_and_b32 s30, s30, 0x380
	v_or_b32_e32 v0, s30, v40
	v_lshlrev_b32_e32 v42, 2, v0
	v_lshl_add_u64 v[0:1], s[24:25], 0, v[42:43]
	v_add_co_u32_e32 v0, vcc, 0x1000, v0
	s_ashr_i32 s34, s41, 4
	s_nop 0
	v_addc_co_u32_e32 v1, vcc, 0, v1, vcc
	global_load_dword v38, v42, s[24:25]
	global_load_dword v39, v[0:1], off
	s_and_b32 s37, s41, 1
	s_ashr_i32 s35, s34, 31
	s_mul_i32 s25, s34, 0x2800000
	s_mul_hi_i32 s24, s34, 0x2800000
	s_add_u32 s42, s72, s25
	s_addc_u32 s43, s73, s24
	s_cmp_eq_u32 s37, 0
	s_cselect_b64 s[24:25], -1, 0
	s_lshl_b32 s36, s30, 1
	s_add_u32 s42, s42, s36
	s_addc_u32 s43, s43, 0
	v_lshlrev_b32_e32 v42, 1, v40
	v_cndmask_b32_e64 v0, v104, v41, s[24:25]
	v_lshl_add_u64 v[48:49], s[42:43], 0, v[42:43]
	v_mul_u32_u24_e32 v42, 0x2800, v0
	v_lshl_add_u64 v[0:1], v[48:49], 0, v[42:43]
	v_cndmask_b32_e64 v4, v106, v105, s[24:25]
	v_add_co_u32_e32 v2, vcc, s39, v0
	v_mul_u32_u24_e32 v42, 0x2800, v4
	s_nop 0
	v_addc_co_u32_e32 v3, vcc, 0, v1, vcc
	v_lshl_add_u64 v[4:5], v[48:49], 0, v[42:43]
	v_add_co_u32_e32 v6, vcc, s39, v4
	s_waitcnt lgkmcnt(0)
	s_barrier
	v_addc_co_u32_e32 v7, vcc, 0, v5, vcc
	global_load_ushort v45, v[2:3], off offset:2048
	global_load_ushort v47, v[6:7], off offset:2048
	v_cndmask_b32_e64 v2, v108, v107, s[24:25]
	v_mul_u32_u24_e32 v42, 0x2800, v2
	v_lshl_add_u64 v[2:3], v[48:49], 0, v[42:43]
	v_cndmask_b32_e64 v8, v110, v109, s[24:25]
	v_add_co_u32_e32 v6, vcc, s39, v2
	v_mul_u32_u24_e32 v42, 0x2800, v8
	s_nop 0
	v_addc_co_u32_e32 v7, vcc, 0, v3, vcc
	v_lshl_add_u64 v[8:9], v[48:49], 0, v[42:43]
	v_cndmask_b32_e64 v12, v112, v111, s[24:25]
	v_add_co_u32_e32 v10, vcc, s39, v8
	v_mul_u32_u24_e32 v42, 0x2800, v12
	s_nop 0
	v_addc_co_u32_e32 v11, vcc, 0, v9, vcc
	v_lshl_add_u64 v[12:13], v[48:49], 0, v[42:43]
	v_add_co_u32_e32 v14, vcc, s39, v12
	v_cndmask_b32_e64 v18, v118, v117, s[24:25]
	s_nop 0
	v_addc_co_u32_e32 v15, vcc, 0, v13, vcc
	global_load_ushort v50, v[6:7], off offset:2048
	global_load_ushort v51, v[10:11], off offset:2048
	global_load_ushort v52, v[14:15], off offset:2048
	v_cndmask_b32_e64 v6, v114, v113, s[24:25]
	v_mul_u32_u24_e32 v42, 0x2800, v6
	v_lshl_add_u64 v[6:7], v[48:49], 0, v[42:43]
	v_cndmask_b32_e64 v14, v116, v115, s[24:25]
	v_add_co_u32_e32 v10, vcc, s39, v6
	v_mul_u32_u24_e32 v42, 0x2800, v14
	s_nop 0
	v_addc_co_u32_e32 v11, vcc, 0, v7, vcc
	v_lshl_add_u64 v[14:15], v[48:49], 0, v[42:43]
	v_add_co_u32_e32 v16, vcc, s39, v14
	v_mul_u32_u24_e32 v42, 0x2800, v18
	s_nop 0
	v_addc_co_u32_e32 v17, vcc, 0, v15, vcc
	v_lshl_add_u64 v[18:19], v[48:49], 0, v[42:43]
	v_add_co_u32_e32 v20, vcc, s39, v18
	v_cndmask_b32_e64 v24, v126, v125, s[24:25]
	s_nop 0
	v_addc_co_u32_e32 v21, vcc, 0, v19, vcc
	global_load_ushort v53, v[10:11], off offset:2048
	global_load_ushort v54, v[16:17], off offset:2048
	global_load_ushort v55, v[20:21], off offset:2048
	v_cndmask_b32_e64 v10, v120, v119, s[24:25]
	v_mul_u32_u24_e32 v42, 0x2800, v10
	v_lshl_add_u64 v[10:11], v[48:49], 0, v[42:43]
	v_cndmask_b32_e64 v20, v122, v121, s[24:25]
	v_add_co_u32_e32 v16, vcc, s39, v10
	v_mul_u32_u24_e32 v42, 0x2800, v20
	s_nop 0
	v_addc_co_u32_e32 v17, vcc, 0, v11, vcc
	v_lshl_add_u64 v[20:21], v[48:49], 0, v[42:43]
	v_add_co_u32_e32 v22, vcc, s39, v20
	v_cndmask_b32_e64 v28, v128, v127, s[24:25]
	s_nop 0
	v_addc_co_u32_e32 v23, vcc, 0, v21, vcc
	global_load_ushort v56, v[16:17], off offset:2048
	global_load_ushort v57, v[22:23], off offset:2048
	v_cndmask_b32_e64 v16, v124, v123, s[24:25]
	v_mul_u32_u24_e32 v42, 0x2800, v16
	v_lshl_add_u64 v[16:17], v[48:49], 0, v[42:43]
	v_add_co_u32_e32 v22, vcc, s39, v16
	v_mul_u32_u24_e32 v42, 0x2800, v24
	s_nop 0
	v_addc_co_u32_e32 v23, vcc, 0, v17, vcc
	v_lshl_add_u64 v[24:25], v[48:49], 0, v[42:43]
	v_add_co_u32_e32 v26, vcc, s39, v24
	v_mul_u32_u24_e32 v42, 0x2800, v28
	s_nop 0
	v_addc_co_u32_e32 v27, vcc, 0, v25, vcc
	v_lshl_add_u64 v[28:29], v[48:49], 0, v[42:43]
	v_add_co_u32_e32 v30, vcc, s39, v28
	v_cndmask_b32_e64 v34, v134, v133, s[24:25]
	s_nop 0
	v_addc_co_u32_e32 v31, vcc, 0, v29, vcc
	global_load_ushort v58, v[22:23], off offset:2048
	global_load_ushort v59, v[26:27], off offset:2048
	global_load_ushort v60, v[30:31], off offset:2048
	v_cndmask_b32_e64 v22, v130, v129, s[24:25]
	v_mul_u32_u24_e32 v42, 0x2800, v22
	v_lshl_add_u64 v[22:23], v[48:49], 0, v[42:43]
	v_cndmask_b32_e64 v30, v132, v131, s[24:25]
	v_add_co_u32_e32 v26, vcc, s39, v22
	v_mul_u32_u24_e32 v42, 0x2800, v30
	s_nop 0
	v_addc_co_u32_e32 v27, vcc, 0, v23, vcc
	v_lshl_add_u64 v[30:31], v[48:49], 0, v[42:43]
	v_add_co_u32_e32 v32, vcc, s39, v30
	v_mul_u32_u24_e32 v42, 0x2800, v34
	s_nop 0
	v_addc_co_u32_e32 v33, vcc, 0, v31, vcc
	v_lshl_add_u64 v[34:35], v[48:49], 0, v[42:43]
	v_add_co_u32_e32 v36, vcc, s39, v34
	s_lshl_b32 s30, s37, 11
	s_nop 0
	v_addc_co_u32_e32 v37, vcc, 0, v35, vcc
	global_load_ushort v42, v[26:27], off offset:2048
	global_load_ushort v61, v[32:33], off offset:2048
	global_load_ushort v62, v[36:37], off offset:2048
	v_lshl_add_u64 v[26:27], v[6:7], 0, s[30:31]
	v_lshl_add_u64 v[32:33], v[14:15], 0, s[30:31]
	v_lshl_add_u64 v[36:37], v[18:19], 0, s[30:31]
	global_load_ushort v207, v[26:27], off offset:2048
	global_load_ushort v209, v[14:15], off
	global_load_ushort v210, v[32:33], off offset:2048
	global_load_ushort v211, v[18:19], off
	global_load_ushort v212, v[36:37], off offset:2048
	v_lshl_add_u64 v[14:15], v[22:23], 0, s[30:31]
	v_lshl_add_u64 v[18:19], v[30:31], 0, s[30:31]
	v_lshl_add_u64 v[26:27], v[34:35], 0, s[30:31]
	global_load_ushort v219, v[14:15], off offset:2048
	global_load_ushort v220, v[30:31], off
	global_load_ushort v221, v[18:19], off offset:2048
	global_load_ushort v222, v[34:35], off
	global_load_ushort v223, v[26:27], off offset:2048
	s_waitcnt vmcnt(26)
; __device__ __forceinline__ float frcp(float x) { return __builtin_amdgcn_rcpf(x); }
; #define HG_ISSUE(t0n) do { _Pragma("unroll") for (int i = 0; i < 16; ++i) { const int tk = (t0n) + (dir ? 63 - (i0 + i) : (i0 + i)); const bf16_t* pr = Pb + (size_t)tk * HGP + h * 128 + dcol; \
;         rq[i] = pr[0]; rf[i] = pr[1024 * (1 + dir)]; rv[i] = pr[3072]; } } while (0)
; __device__ __forceinline__ void hgrn_chain(LAS unsigned char* lds, int cid, bf16_t* P1, const float* hg_lb, bf16_t* Ob, int ldo, int ocbase, int ocdir) {
;     ...
;     const int dcol = tid & 127, qtr = tid >> 7, i0 = qtr * 16;
;     const float lbv = frcp(1.0f + __expf(hg_lb[h * 128 + dcol] - hg_lb[1024 + h * 128 + dcol]));
;     f32x4 st[8];
; #pragma unroll
;     for (int i = 0; i < 8; ++i) st[i] = (f32x4){0.f, 0.f, 0.f, 0.f};
;     bf16_t* Pb = P1 + (size_t)b * SEQ * HGP;
;     __syncthreads();
;     unsigned short rq[16], rf[16], rv[16];
;     ...
;     HG_ISSUE((dir ? 63 : 0) * 64);
	v_sub_f32_e32 v14, v38, v39
	v_mul_f32_e32 v30, 0x3fb8aa3b, v14
	v_lshl_add_u64 v[14:15], v[0:1], 0, s[30:31]
	v_lshl_add_u64 v[18:19], v[4:5], 0, s[30:31]
	v_lshl_add_u64 v[26:27], v[2:3], 0, s[30:31]
	global_load_ushort v179, v[0:1], off
	global_load_ushort v180, v[14:15], off offset:2048
	global_load_ushort v181, v[4:5], off
	global_load_ushort v182, v[18:19], off offset:2048
	global_load_ushort v183, v[2:3], off
	global_load_ushort v185, v[26:27], off offset:2048
	v_lshl_add_u64 v[0:1], v[8:9], 0, s[30:31]
	v_lshl_add_u64 v[2:3], v[12:13], 0, s[30:31]
	global_load_ushort v203, v[8:9], off
	global_load_ushort v204, v[0:1], off offset:2048
	global_load_ushort v205, v[12:13], off
	global_load_ushort v206, v[2:3], off offset:2048
	global_load_ushort v208, v[6:7], off
	v_lshl_add_u64 v[0:1], v[10:11], 0, s[30:31]
	v_lshl_add_u64 v[2:3], v[20:21], 0, s[30:31]
	v_lshl_add_u64 v[4:5], v[16:17], 0, s[30:31]
	global_load_ushort v213, v[10:11], off
	global_load_ushort v214, v[0:1], off offset:2048
	global_load_ushort v215, v[20:21], off
	global_load_ushort v216, v[2:3], off offset:2048
	global_load_ushort v217, v[16:17], off
	global_load_ushort v218, v[4:5], off offset:2048
	v_lshl_add_u64 v[0:1], v[24:25], 0, s[30:31]
	v_lshl_add_u64 v[2:3], v[28:29], 0, s[30:31]
	global_load_ushort v224, v[24:25], off
	global_load_ushort v225, v[0:1], off offset:2048
	global_load_ushort v226, v[28:29], off
	global_load_ushort v227, v[2:3], off offset:2048
	global_load_ushort v228, v[22:23], off
	v_exp_f32_e32 v0, v30
	s_lshl_b32 s44, s37, 10
	s_lshl_b64 s[34:35], s[34:35], 12
	s_add_u32 s30, s72, s30
	v_add_f32_e32 v0, 1.0, v0
	s_waitcnt vmcnt(44)
	v_lshl_or_b32 v33, v51, 16, v50
	v_rcp_f32_e32 v50, v0
	s_addc_u32 s37, s73, 0
	s_add_u32 s36, s30, s36
	v_lshl_or_b32 v32, v47, 16, v45
	s_addc_u32 s37, s37, 0
	v_mov_b32_e32 v45, v43
	v_lshl_add_u64 v[0:1], s[36:37], 0, v[44:45]
	v_mov_b32_e32 v47, v43
	s_waitcnt vmcnt(42)
	v_lshl_or_b32 v34, v53, 16, v52
	s_waitcnt vmcnt(40)
	v_lshl_or_b32 v35, v55, 16, v54
	v_sub_f32_e32 v52, 1.0, v50
	v_lshl_add_u64 v[54:55], v[0:1], 0, v[46:47]
	v_mov_b32_e32 v0, 0
	s_mov_b32 s42, 1
	s_waitcnt vmcnt(38)
	v_lshl_or_b32 v36, v57, 16, v56
	v_cndmask_b32_e64 v184, v142, v140, s[24:25]
	v_cndmask_b32_e64 v186, v145, v41, s[24:25]
	v_cndmask_b32_e64 v187, v146, v105, s[24:25]
	v_cndmask_b32_e64 v188, v147, v107, s[24:25]
	v_cndmask_b32_e64 v189, v148, v109, s[24:25]
	v_cndmask_b32_e64 v190, v149, v111, s[24:25]
	v_cndmask_b32_e64 v191, v150, v113, s[24:25]
	v_cndmask_b32_e64 v192, v151, v115, s[24:25]
	v_cndmask_b32_e64 v193, v152, v117, s[24:25]
	v_cndmask_b32_e64 v194, v153, v119, s[24:25]
	v_cndmask_b32_e64 v195, v154, v121, s[24:25]
	s_waitcnt vmcnt(36)
	v_lshl_or_b32 v37, v59, 16, v58
	v_cndmask_b32_e64 v196, v155, v123, s[24:25]
	v_cndmask_b32_e64 v197, v156, v125, s[24:25]
	v_cndmask_b32_e64 v198, v157, v127, s[24:25]
	v_cndmask_b32_e64 v199, v158, v129, s[24:25]
	v_cndmask_b32_e64 v201, v159, v131, s[24:25]
	v_cndmask_b32_e64 v202, v160, v133, s[24:25]
	v_mov_b32_e32 v51, v50
	v_mov_b32_e32 v53, v52
	s_mov_b32 s43, 62
	s_lshl_b32 s30, s44, 1
	v_mov_b32_e32 v1, v0
	v_mov_b64_e32 v[2:3], 0
	v_mov_b64_e32 v[4:5], 0
	v_mov_b64_e32 v[6:7], 0
	v_mov_b64_e32 v[8:9], 0
	v_mov_b32_e32 v10, v0
	s_waitcnt vmcnt(34)
	v_lshl_or_b32 v38, v42, 16, v60
	v_mov_b32_e32 v11, v0
	s_waitcnt vmcnt(32)
	v_lshl_or_b32 v39, v62, 16, v61
	v_mov_b32_e32 v16, v0
	v_mov_b32_e32 v17, v0
	v_mov_b64_e32 v[18:19], 0
	v_mov_b64_e32 v[12:13], 0
	v_mov_b64_e32 v[14:15], 0
	v_mov_b64_e32 v[24:25], 0
	v_mov_b64_e32 v[26:27], 0
	v_mov_b64_e32 v[20:21], 0
	v_mov_b64_e32 v[22:23], 0
	v_mov_b64_e32 v[28:29], 0
	v_mov_b64_e32 v[30:31], 0
	s_branch .LBB0_1716

;     __device__ __forceinline__ long offA(const Unit& u) const { return (long)(u.z / zdiv) * sAo + (long)(u.z % zdiv) * sAi + (long)u.pm * BM * lda; }
;     __device__ __forceinline__ long offB(const Unit& u) const { return (long)(u.z / zdiv) * sBo + (long)(u.z % zdiv) * sBi + (long)u.pn * BM * ldb; }
; template <class Epi, bool ALIGN_EPI>
; __device__ __forceinline__ void gemm_phase(LAS unsigned char* lds, LAS unsigned char* xl, const Gemm g, const Order& S, Epi& E) {
;     ...
;         const bool has_next = S.next(ui + 1, nxt);
;         const char* nA = has_next ? (const char*)g.A + 2 * g.offA(nxt) : cA; const char* nB = has_next ? (const char*)g.Bt + 2 * g.offB(nxt) : cB;
;     ...
;         for (int a = 0; a < 2; ++a)
; #pragma unroll
;             for (int b = 0; b < 2; ++b)
; #pragma unroll
;                 for (int m = 0; m < 4; ++m)
; #pragma unroll
;                     for (int n = 0; n < 2; ++n) acc[a][b][m][n] = (f32x4){0.f, 0.f, 0.f, 0.f};
;         cur = nxt; cA = nA; cB = nB; ++ui;
.LBB0_1847:
	s_ashr_i32 s15, s14, 31
	s_lshl_b64 s[18:19], s[14:15], 19
	s_add_u32 s18, s66, s18
	s_addc_u32 s19, s67, s19
	s_and_b64 s[20:21], s[2:3], exec
	s_cselect_b32 s15, s19, s25
	s_cselect_b32 s23, s18, s24
	s_ashr_i32 s17, s16, 31
	s_lshl_b64 s[20:21], s[16:17], 19
	s_add_u32 s20, s64, s20
	s_addc_u32 s21, s65, s21
	s_and_b64 s[30:31], s[2:3], exec
	s_cselect_b32 s17, s21, s29
	s_cselect_b32 s49, s20, s28
	s_add_u32 s24, s24, 0x40080
	s_addc_u32 s25, s25, 0
	s_add_u32 s50, s28, 0x100
	v_mov_b32_e32 v0, 0
	s_addc_u32 s51, s29, 0
	s_mov_b32 s52, -2
	v_mov_b32_e32 v1, v0
	v_mov_b64_e32 v[2:3], 0
	v_mov_b64_e32 v[4:5], 0
	v_mov_b64_e32 v[6:7], 0
	v_mov_b64_e32 v[16:17], 0
	v_mov_b64_e32 v[18:19], 0
	v_mov_b64_e32 v[20:21], 0
	v_mov_b64_e32 v[22:23], 0
	v_mov_b64_e32 v[32:33], 0
	v_mov_b64_e32 v[34:35], 0
	v_mov_b64_e32 v[36:37], 0
	v_mov_b64_e32 v[38:39], 0
	v_mov_b64_e32 v[48:49], 0
	v_mov_b64_e32 v[50:51], 0
	v_mov_b64_e32 v[52:53], 0
	v_mov_b64_e32 v[54:55], 0
	v_mov_b64_e32 v[8:9], 0
	v_mov_b64_e32 v[10:11], 0
	v_mov_b64_e32 v[12:13], 0
	v_mov_b64_e32 v[14:15], 0
	v_mov_b64_e32 v[24:25], 0
	v_mov_b64_e32 v[26:27], 0
	v_mov_b64_e32 v[28:29], 0
	v_mov_b64_e32 v[30:31], 0
	v_mov_b64_e32 v[40:41], 0
	v_mov_b64_e32 v[42:43], 0
	v_mov_b64_e32 v[44:45], 0
	v_mov_b64_e32 v[46:47], 0
	v_mov_b64_e32 v[56:57], 0
	v_mov_b64_e32 v[58:59], 0
	v_mov_b64_e32 v[60:61], 0
	v_mov_b64_e32 v[62:63], 0
	v_mov_b64_e32 v[64:65], 0
	v_mov_b64_e32 v[66:67], 0
	v_mov_b64_e32 v[68:69], 0
	v_mov_b64_e32 v[70:71], 0
	v_mov_b64_e32 v[80:81], 0
	v_mov_b64_e32 v[82:83], 0
	v_mov_b64_e32 v[84:85], 0
	v_mov_b64_e32 v[86:87], 0
	v_mov_b64_e32 v[96:97], 0
	v_mov_b64_e32 v[98:99], 0
	v_mov_b64_e32 v[100:101], 0
	v_mov_b64_e32 v[102:103], 0
	v_mov_b64_e32 v[112:113], 0
	v_mov_b64_e32 v[114:115], 0
	v_mov_b64_e32 v[116:117], 0
	v_mov_b64_e32 v[118:119], 0
	v_mov_b64_e32 v[72:73], 0
	v_mov_b64_e32 v[74:75], 0
	v_mov_b64_e32 v[76:77], 0
	v_mov_b64_e32 v[78:79], 0
	v_mov_b64_e32 v[88:89], 0
	v_mov_b64_e32 v[90:91], 0
	v_mov_b64_e32 v[92:93], 0
	v_mov_b64_e32 v[94:95], 0
	v_mov_b64_e32 v[104:105], 0
	v_mov_b64_e32 v[106:107], 0
	v_mov_b64_e32 v[108:109], 0
	v_mov_b64_e32 v[110:111], 0
	v_mov_b64_e32 v[132:133], 0
	v_mov_b64_e32 v[134:135], 0
	v_mov_b64_e32 v[136:137], 0
	v_mov_b64_e32 v[138:139], 0

; #define LAS __attribute__((address_space(3)))
;     __device__ __forceinline__ long offA(const Unit& u) const { return (long)(u.z / zdiv) * sAo + (long)(u.z % zdiv) * sAi + (long)u.pm * BM * lda; }
;     __device__ __forceinline__ long offB(const Unit& u) const { return (long)(u.z / zdiv) * sBo + (long)(u.z % zdiv) * sBi + (long)u.pn * BM * ldb; }
; template <class Epi, bool ALIGN_EPI>
; __device__ __forceinline__ void gemm_phase(LAS unsigned char* lds, LAS unsigned char* xl, const Gemm g, const Order& S, Epi& E) {
;     ...
;         const bool has_next = S.next(ui + 1, nxt);
;         const char* nA = has_next ? (const char*)g.A + 2 * g.offA(nxt) : cA; const char* nB = has_next ? (const char*)g.Bt + 2 * g.offB(nxt) : cB;
;         for (int t = 0; t < nt; t += 2) {
;             const bool last = (t == nt - 2);
;             const char* a1 = cA + (size_t)(t + 1) * kstep;
;             const char* a2 = last ? nA : cA + (size_t)(t + 2) * kstep; const char* b2 = last ? nB : cB + (size_t)(t + 2) * kstep;
;             const char* a3 = a2 + kstep; const char* b3 = b2 + kstep;
;             if constexpr (Epi::PSLDS) { if (last) {
;                 const char* psrc = (const char*)(E.PS + (size_t)((cur.z / g.zdiv) * g.psz + cur.pm) * (BM * 16)) + tid * 16;
; #pragma unroll
;                 for (int _i = 0; _i < 2; ++_i) __builtin_amdgcn_global_load_lds((const unsigned*)(psrc + _i * 8192), (LAS unsigned*)(xl + 8192 + ldsw + _i * 8192), 16, 0, 0); } }
;     ...
;         for (int a = 0; a < 2; ++a)
; #pragma unroll
;             for (int b = 0; b < 2; ++b)
; #pragma unroll
;                 for (int m = 0; m < 4; ++m)
; #pragma unroll
;                     for (int n = 0; n < 2; ++n) acc[a][b][m][n] = (f32x4){0.f, 0.f, 0.f, 0.f};
;         cur = nxt; cA = nA; cB = nB; ++ui;
.LBB0_2146:
	s_ashr_i32 s21, s20, 31
	s_lshl_b64 s[24:25], s[20:21], 19
	v_readlane_b32 s28, v253, 21
	v_readlane_b32 s29, v253, 22
	s_add_u32 s24, s28, s24
	s_addc_u32 s25, s29, s25
	s_and_b64 s[28:29], s[0:1], exec
	s_cselect_b32 s21, s25, s5
	s_cselect_b32 s52, s24, s4
	s_ashr_i32 s23, s22, 31
	s_lshl_b64 s[28:29], s[22:23], 19
	s_add_u32 s28, s17, s28
	s_addc_u32 s29, s19, s29
	s_and_b64 s[34:35], s[0:1], exec
	s_cselect_b32 s23, s29, s31
	s_cselect_b32 s53, s28, s30
	s_ashr_i32 s3, s2, 31
	s_lshl_b64 s[34:35], s[2:3], 14
	s_add_u32 s4, s4, 0x40080
	s_addc_u32 s5, s5, 0
	v_lshl_add_u64 v[146:147], v[136:137], 0, s[34:35]
	s_add_u32 s3, s30, 0x100
	v_mov_b32_e32 v0, 0
	v_lshl_add_u64 v[148:149], v[146:147], 0, s[14:15]
	s_addc_u32 s54, s31, 0
	s_mov_b32 s55, -2
	v_mov_b32_e32 v1, v0
	v_mov_b64_e32 v[2:3], 0
	v_mov_b64_e32 v[4:5], 0
	v_mov_b64_e32 v[6:7], 0
	v_mov_b64_e32 v[16:17], 0
	v_mov_b64_e32 v[18:19], 0
	v_mov_b64_e32 v[20:21], 0
	v_mov_b64_e32 v[22:23], 0
	v_mov_b64_e32 v[32:33], 0
	v_mov_b64_e32 v[34:35], 0
	v_mov_b64_e32 v[36:37], 0
	v_mov_b64_e32 v[38:39], 0
	v_mov_b64_e32 v[48:49], 0
	v_mov_b64_e32 v[50:51], 0
	v_mov_b64_e32 v[52:53], 0
	v_mov_b64_e32 v[54:55], 0
	v_mov_b64_e32 v[8:9], 0
	v_mov_b64_e32 v[10:11], 0
	v_mov_b64_e32 v[12:13], 0
	v_mov_b64_e32 v[14:15], 0
	v_mov_b64_e32 v[24:25], 0
	v_mov_b64_e32 v[26:27], 0
	v_mov_b64_e32 v[28:29], 0
	v_mov_b64_e32 v[30:31], 0
	v_mov_b64_e32 v[40:41], 0
	v_mov_b64_e32 v[42:43], 0
	v_mov_b64_e32 v[44:45], 0
	v_mov_b64_e32 v[46:47], 0
	v_mov_b64_e32 v[56:57], 0
	v_mov_b64_e32 v[58:59], 0
	v_mov_b64_e32 v[60:61], 0
	v_mov_b64_e32 v[62:63], 0
	v_mov_b64_e32 v[64:65], 0
	v_mov_b64_e32 v[66:67], 0
	v_mov_b64_e32 v[68:69], 0
	v_mov_b64_e32 v[70:71], 0
	v_mov_b64_e32 v[80:81], 0
	v_mov_b64_e32 v[82:83], 0
	v_mov_b64_e32 v[84:85], 0
	v_mov_b64_e32 v[86:87], 0
	v_mov_b64_e32 v[96:97], 0
	v_mov_b64_e32 v[98:99], 0
	v_mov_b64_e32 v[100:101], 0
	v_mov_b64_e32 v[102:103], 0
	v_mov_b64_e32 v[112:113], 0
	v_mov_b64_e32 v[114:115], 0
	v_mov_b64_e32 v[116:117], 0
	v_mov_b64_e32 v[118:119], 0
	v_mov_b64_e32 v[72:73], 0
	v_mov_b64_e32 v[74:75], 0
	v_mov_b64_e32 v[76:77], 0
	v_mov_b64_e32 v[78:79], 0
	v_mov_b64_e32 v[88:89], 0
	v_mov_b64_e32 v[90:91], 0
	v_mov_b64_e32 v[92:93], 0
	v_mov_b64_e32 v[94:95], 0
	v_mov_b64_e32 v[104:105], 0
	v_mov_b64_e32 v[106:107], 0
	v_mov_b64_e32 v[108:109], 0
	v_mov_b64_e32 v[110:111], 0
	v_mov_b64_e32 v[120:121], 0
	v_mov_b64_e32 v[122:123], 0
	v_mov_b64_e32 v[124:125], 0
	v_mov_b64_e32 v[126:127], 0
	s_branch .LBB0_2148

;     __device__ __forceinline__ long offA(const Unit& u) const { return (long)(u.z / zdiv) * sAo + (long)(u.z % zdiv) * sAi + (long)u.pm * BM * lda; }
;     __device__ __forceinline__ long offB(const Unit& u) const { return (long)(u.z / zdiv) * sBo + (long)(u.z % zdiv) * sBi + (long)u.pn * BM * ldb; }
; template <class Epi, bool ALIGN_EPI>
; __device__ __forceinline__ void gemm_phase(LAS unsigned char* lds, LAS unsigned char* xl, const Gemm g, const Order& S, Epi& E) {
;     ...
;         const bool has_next = S.next(ui + 1, nxt);
;         const char* nA = has_next ? (const char*)g.A + 2 * g.offA(nxt) : cA; const char* nB = has_next ? (const char*)g.Bt + 2 * g.offB(nxt) : cB;
;     ...
;         for (int a = 0; a < 2; ++a)
; #pragma unroll
;             for (int b = 0; b < 2; ++b)
; #pragma unroll
;                 for (int m = 0; m < 4; ++m)
; #pragma unroll
;                     for (int n = 0; n < 2; ++n) acc[a][b][m][n] = (f32x4){0.f, 0.f, 0.f, 0.f};
;         cur = nxt; cA = nA; cB = nB; ++ui;
.LBB0_2229:
	s_add_u32 s18, s18, 0xb0080
	s_addc_u32 s19, s19, 0
	s_add_u32 s46, s20, 0x100
	v_mov_b32_e32 v0, 0
	s_addc_u32 s47, s21, 0
	s_mov_b32 s48, -2
	v_mov_b32_e32 v1, v0
	v_mov_b64_e32 v[2:3], 0
	v_mov_b64_e32 v[4:5], 0
	v_mov_b64_e32 v[6:7], 0
	v_mov_b64_e32 v[16:17], 0
	v_mov_b64_e32 v[18:19], 0
	v_mov_b64_e32 v[20:21], 0
	v_mov_b64_e32 v[22:23], 0
	v_mov_b64_e32 v[32:33], 0
	v_mov_b64_e32 v[34:35], 0
	v_mov_b64_e32 v[36:37], 0
	v_mov_b64_e32 v[38:39], 0
	v_mov_b64_e32 v[48:49], 0
	v_mov_b64_e32 v[50:51], 0
	v_mov_b64_e32 v[52:53], 0
	v_mov_b64_e32 v[54:55], 0
	v_mov_b64_e32 v[8:9], 0
	v_mov_b64_e32 v[10:11], 0
	v_mov_b64_e32 v[12:13], 0
	v_mov_b64_e32 v[14:15], 0
	v_mov_b64_e32 v[24:25], 0
	v_mov_b64_e32 v[26:27], 0
	v_mov_b64_e32 v[28:29], 0
	v_mov_b64_e32 v[30:31], 0
	v_mov_b64_e32 v[40:41], 0
	v_mov_b64_e32 v[42:43], 0
	v_mov_b64_e32 v[44:45], 0
	v_mov_b64_e32 v[46:47], 0
	v_mov_b64_e32 v[56:57], 0
	v_mov_b64_e32 v[58:59], 0
	v_mov_b64_e32 v[60:61], 0
	v_mov_b64_e32 v[62:63], 0
	v_mov_b64_e32 v[64:65], 0
	v_mov_b64_e32 v[66:67], 0
	v_mov_b64_e32 v[68:69], 0
	v_mov_b64_e32 v[70:71], 0
	v_mov_b64_e32 v[80:81], 0
	v_mov_b64_e32 v[82:83], 0
	v_mov_b64_e32 v[84:85], 0
	v_mov_b64_e32 v[86:87], 0
	v_mov_b64_e32 v[96:97], 0
	v_mov_b64_e32 v[98:99], 0
	v_mov_b64_e32 v[100:101], 0
	v_mov_b64_e32 v[102:103], 0
	v_mov_b64_e32 v[112:113], 0
	v_mov_b64_e32 v[114:115], 0
	v_mov_b64_e32 v[116:117], 0
	v_mov_b64_e32 v[118:119], 0
	v_mov_b64_e32 v[72:73], 0
	v_mov_b64_e32 v[74:75], 0
	v_mov_b64_e32 v[76:77], 0
	v_mov_b64_e32 v[78:79], 0
	v_mov_b64_e32 v[88:89], 0
	v_mov_b64_e32 v[90:91], 0
	v_mov_b64_e32 v[92:93], 0
	v_mov_b64_e32 v[94:95], 0
	v_mov_b64_e32 v[104:105], 0
	v_mov_b64_e32 v[106:107], 0
	v_mov_b64_e32 v[108:109], 0
	v_mov_b64_e32 v[110:111], 0
	v_mov_b64_e32 v[132:133], 0
	v_mov_b64_e32 v[134:135], 0
	v_mov_b64_e32 v[136:137], 0
	v_mov_b64_e32 v[138:139], 0
